# attention QK^T: LDS K-fragment reads run 11 ahead of the MFMAs in a ring of unused VGPRs (attnA x2, attnC x4 regions)
# speedup vs baseline: 1.0240x; 1.0024x over previous
; __device__ __forceinline__ void attnA_item(const Frame& F, const Args& a, int item) {
;     ...
;     const int qq = 16 * (F.wave & 3) + fr;
;     const int qpos = (n0 + hb) * 64 + qq;
;     const size_t qrow = rowbase + (size_t)qpos * d + r;
;     bf16x8 qf[4];
; #pragma unroll
;     for (int ks = 0; ks < 4; ++ks) qf[ks] = *(const bf16x8*)(proj + qrow * NIN + C_Q + h * 128 + 32 * ks + 8 * fq);
;     __syncthreads();
.LBB0_292:
	s_or_b64 exec, exec, s[72:73]
	s_add_i32 s12, s12, s95
	v_or_b32_e32 v66, s12, v85
	v_lshlrev_b64 v[0:1], s11, v[66:67]
	v_lshl_add_u64 v[60:61], v[0:1], 0, s[8:9]
	v_mov_b64_e32 v[0:1], s[96:97]
	v_mad_u64_u32 v[0:1], s[8:9], v60, s93, v[0:1]
	v_mov_b32_e32 v2, v1
	v_mad_u64_u32 v[2:3], s[8:9], v61, s93, v[2:3]
	v_mov_b32_e32 v1, v2
	v_lshl_add_u64 v[0:1], s[0:1], 1, v[0:1]
	v_mov_b32_e32 v71, v67
	v_lshl_add_u64 v[0:1], v[0:1], 0, v[70:71]
	global_load_dwordx4 v[56:59], v[0:1], off
	global_load_dwordx4 v[52:55], v[0:1], off offset:64
	global_load_dwordx4 v[48:51], v[0:1], off offset:128
	s_nop 0
	global_load_dwordx4 v[0:3], v[0:1], off offset:192
	s_waitcnt lgkmcnt(0)
	s_barrier
; #define LAS __attribute__((address_space(3)))
; template <int NCT>
; __device__ __forceinline__ void qk_accum(f32x4 (&s)[NCT], const LAS unsigned char* Kt, int key_row0, const bf16x8 (&qf)[4], int fr, int fq) {
; #pragma unroll
;     for (int ct = 0; ct < NCT; ++ct)
; #pragma unroll
;         for (int ks = 0; ks < 4; ++ks) { const bf16x8 kf = *(const LAS bf16x8*)(Kt + (key_row0 + 16 * ct + fr) * AT_PITCH + 64 * ks + 16 * fq);
;             s[ct] = __builtin_amdgcn_mfma_f32_16x16x32_bf16(kf, qf[ks], s[ct], 0, 0, 0); if (ks == 3 && (ct & 1)) asm volatile("" ::: "memory"); }
; }
	s_sub_i32 s1, s12, 64
	s_cmp_lg_u32 s12, 0
	v_readlane_b32 s14, v242, 44
	s_cselect_b64 s[8:9], -1, 0
	v_readlane_b32 s15, v242, 45
	s_and_b64 s[14:15], s[14:15], s[8:9]
	ds_read_b128 v[208:211], v195
	ds_read_b128 v[212:215], v195 offset:64
	ds_read_b128 v[216:219], v195 offset:128
	ds_read_b128 v[220:223], v195 offset:192
	ds_read_b128 v[224:227], v195 offset:4352
	ds_read_b128 v[228:231], v195 offset:4416
	ds_read_b128 v[232:235], v195 offset:4480
	ds_read_b128 v[236:239], v195 offset:4544
	ds_read_b128 v[244:247], v195 offset:8704
	ds_read_b128 v[248:251], v195 offset:8768
	ds_read_b128 v[252:255], v195 offset:8832
	s_waitcnt vmcnt(0)
	s_waitcnt lgkmcnt(10)
	v_mfma_f32_16x16x32_bf16 v[4:7], v[208:211], v[56:59], 0
	ds_read_b128 v[208:211], v195 offset:8896
	s_waitcnt lgkmcnt(10)
	v_mfma_f32_16x16x32_bf16 v[4:7], v[212:215], v[52:55], v[4:7]
	ds_read_b128 v[212:215], v195 offset:13056
	s_waitcnt lgkmcnt(10)
	v_mfma_f32_16x16x32_bf16 v[4:7], v[216:219], v[48:51], v[4:7]
	ds_read_b128 v[216:219], v195 offset:13120
	s_waitcnt lgkmcnt(10)
	v_mfma_f32_16x16x32_bf16 v[44:47], v[220:223], v[0:3], v[4:7]
	ds_read_b128 v[220:223], v195 offset:13184
	s_waitcnt lgkmcnt(10)
	v_mfma_f32_16x16x32_bf16 v[4:7], v[224:227], v[56:59], 0
	ds_read_b128 v[224:227], v195 offset:13248
	s_waitcnt lgkmcnt(10)
	v_mfma_f32_16x16x32_bf16 v[4:7], v[228:231], v[52:55], v[4:7]
	ds_read_b128 v[228:231], v195 offset:17408
	s_waitcnt lgkmcnt(10)
	v_mfma_f32_16x16x32_bf16 v[4:7], v[232:235], v[48:51], v[4:7]
	ds_read_b128 v[232:235], v195 offset:17472
	s_waitcnt lgkmcnt(10)
	v_mfma_f32_16x16x32_bf16 v[40:43], v[236:239], v[0:3], v[4:7]
	ds_read_b128 v[236:239], v195 offset:17536
	s_waitcnt lgkmcnt(10)
	v_mfma_f32_16x16x32_bf16 v[4:7], v[244:247], v[56:59], 0
	ds_read_b128 v[244:247], v195 offset:17600
	s_waitcnt lgkmcnt(10)
	v_mfma_f32_16x16x32_bf16 v[4:7], v[248:251], v[52:55], v[4:7]
	ds_read_b128 v[248:251], v195 offset:21760
	s_waitcnt lgkmcnt(10)
	v_mfma_f32_16x16x32_bf16 v[4:7], v[252:255], v[48:51], v[4:7]
	ds_read_b128 v[252:255], v195 offset:21824
	s_waitcnt lgkmcnt(10)
	v_mfma_f32_16x16x32_bf16 v[36:39], v[208:211], v[0:3], v[4:7]
	ds_read_b128 v[208:211], v195 offset:21888
	s_waitcnt lgkmcnt(10)
	v_mfma_f32_16x16x32_bf16 v[4:7], v[212:215], v[56:59], 0
	ds_read_b128 v[212:215], v195 offset:21952
	s_waitcnt lgkmcnt(10)
	v_mfma_f32_16x16x32_bf16 v[4:7], v[216:219], v[52:55], v[4:7]
	ds_read_b128 v[216:219], v195 offset:26112
	s_waitcnt lgkmcnt(10)
	v_mfma_f32_16x16x32_bf16 v[4:7], v[220:223], v[48:51], v[4:7]
	ds_read_b128 v[220:223], v195 offset:26176
	s_waitcnt lgkmcnt(10)
	v_mfma_f32_16x16x32_bf16 v[32:35], v[224:227], v[0:3], v[4:7]
	ds_read_b128 v[224:227], v195 offset:26240
	s_waitcnt lgkmcnt(10)
	v_mfma_f32_16x16x32_bf16 v[4:7], v[228:231], v[56:59], 0
	ds_read_b128 v[228:231], v195 offset:26304
	s_waitcnt lgkmcnt(10)
	v_mfma_f32_16x16x32_bf16 v[4:7], v[232:235], v[52:55], v[4:7]
	ds_read_b128 v[232:235], v195 offset:30464
	s_waitcnt lgkmcnt(10)
	v_mfma_f32_16x16x32_bf16 v[4:7], v[236:239], v[48:51], v[4:7]
	ds_read_b128 v[236:239], v195 offset:30528
	s_waitcnt lgkmcnt(10)
	v_mfma_f32_16x16x32_bf16 v[20:23], v[244:247], v[0:3], v[4:7]
	ds_read_b128 v[244:247], v195 offset:30592
	s_waitcnt lgkmcnt(10)
	v_mfma_f32_16x16x32_bf16 v[4:7], v[248:251], v[56:59], 0
	ds_read_b128 v[248:251], v195 offset:30656
	s_waitcnt lgkmcnt(10)
	v_mfma_f32_16x16x32_bf16 v[4:7], v[252:255], v[52:55], v[4:7]
	ds_read_b128 v[252:255], v195 offset:34816
	s_waitcnt lgkmcnt(10)
	v_mfma_f32_16x16x32_bf16 v[4:7], v[208:211], v[48:51], v[4:7]
	ds_read_b128 v[208:211], v195 offset:34880
	s_waitcnt lgkmcnt(10)
	v_mfma_f32_16x16x32_bf16 v[16:19], v[212:215], v[0:3], v[4:7]
	ds_read_b128 v[212:215], v195 offset:34944
	s_waitcnt lgkmcnt(10)
	v_mfma_f32_16x16x32_bf16 v[4:7], v[216:219], v[56:59], 0
	ds_read_b128 v[216:219], v195 offset:35008
	s_waitcnt lgkmcnt(10)
	v_mfma_f32_16x16x32_bf16 v[4:7], v[220:223], v[52:55], v[4:7]
	ds_read_b128 v[220:223], v195 offset:39168
	s_waitcnt lgkmcnt(10)
	v_mfma_f32_16x16x32_bf16 v[4:7], v[224:227], v[48:51], v[4:7]
	ds_read_b128 v[224:227], v195 offset:39232
	s_waitcnt lgkmcnt(10)
	v_mfma_f32_16x16x32_bf16 v[28:31], v[228:231], v[0:3], v[4:7]
	ds_read_b128 v[228:231], v195 offset:39296
	s_waitcnt lgkmcnt(10)
	v_mfma_f32_16x16x32_bf16 v[4:7], v[232:235], v[56:59], 0
	ds_read_b128 v[232:235], v195 offset:39360
	s_waitcnt lgkmcnt(10)
	v_mfma_f32_16x16x32_bf16 v[4:7], v[236:239], v[52:55], v[4:7]
	ds_read_b128 v[236:239], v195 offset:43584
	s_waitcnt lgkmcnt(10)
	v_mfma_f32_16x16x32_bf16 v[4:7], v[244:247], v[48:51], v[4:7]
	ds_read_b128 v[244:247], v195 offset:43520
	s_waitcnt lgkmcnt(10)
	v_mfma_f32_16x16x32_bf16 v[24:27], v[248:251], v[0:3], v[4:7]
	ds_read_b128 v[248:251], v195 offset:43648
	s_waitcnt lgkmcnt(10)
	v_mfma_f32_16x16x32_bf16 v[4:7], v[252:255], v[56:59], 0
	ds_read_b128 v[252:255], v195 offset:43712
	s_waitcnt lgkmcnt(10)
	v_mfma_f32_16x16x32_bf16 v[4:7], v[208:211], v[52:55], v[4:7]
	ds_read_b128 v[208:211], v195 offset:47872
	s_waitcnt lgkmcnt(10)
	v_mfma_f32_16x16x32_bf16 v[4:7], v[212:215], v[48:51], v[4:7]
	ds_read_b128 v[212:215], v195 offset:47936
	s_waitcnt lgkmcnt(10)
	v_mfma_f32_16x16x32_bf16 v[12:15], v[216:219], v[0:3], v[4:7]
	ds_read_b128 v[216:219], v195 offset:48000
	s_waitcnt lgkmcnt(10)
	v_mfma_f32_16x16x32_bf16 v[4:7], v[220:223], v[56:59], 0
	ds_read_b128 v[220:223], v195 offset:48064
	s_waitcnt lgkmcnt(10)
	v_mfma_f32_16x16x32_bf16 v[4:7], v[224:227], v[52:55], v[4:7]
	s_waitcnt lgkmcnt(9)
	v_mfma_f32_16x16x32_bf16 v[4:7], v[228:231], v[48:51], v[4:7]
	s_waitcnt lgkmcnt(8)
	v_mfma_f32_16x16x32_bf16 v[8:11], v[232:235], v[0:3], v[4:7]
	s_waitcnt lgkmcnt(6)
	v_mfma_f32_16x16x32_bf16 v[4:7], v[244:247], v[56:59], 0
	s_waitcnt lgkmcnt(7)
	v_mfma_f32_16x16x32_bf16 v[4:7], v[236:239], v[52:55], v[4:7]
	s_waitcnt lgkmcnt(5)
	v_mfma_f32_16x16x32_bf16 v[4:7], v[248:251], v[48:51], v[4:7]
	s_waitcnt lgkmcnt(4)
	v_mfma_f32_16x16x32_bf16 v[4:7], v[252:255], v[0:3], v[4:7]
	s_waitcnt lgkmcnt(3)
	v_mfma_f32_16x16x32_bf16 v[56:59], v[208:211], v[56:59], 0
	s_waitcnt lgkmcnt(2)
	v_mfma_f32_16x16x32_bf16 v[52:55], v[212:215], v[52:55], v[56:59]
	s_waitcnt lgkmcnt(1)
	v_mfma_f32_16x16x32_bf16 v[48:51], v[216:219], v[48:51], v[52:55]
	s_waitcnt lgkmcnt(0)
	v_mfma_f32_16x16x32_bf16 v[0:3], v[220:223], v[0:3], v[48:51]
	s_nop 2
	v_or_b32_e32 v48, s1, v68
	v_cmp_gt_i32_e32 vcc, s10, v48
	s_and_b64 s[14:15], s[14:15], vcc
	v_mov_b32_e32 v48, 0xf149f2ca
	v_mov_b32_e32 v49, 0xf149f2ca
	s_and_saveexec_b64 s[72:73], s[14:15]
	s_cbranch_execz .LBB0_294
	ds_read_b32 v49, v86
	s_waitcnt lgkmcnt(0)
	v_fmac_f32_e32 v49, 0x3db504f3, v44

; #define LAS __attribute__((address_space(3)))
; template <int NCT>
; __device__ __forceinline__ void qk_accum(f32x4 (&s)[NCT], const LAS unsigned char* Kt, int key_row0, const bf16x8 (&qf)[4], int fr, int fq) {
; #pragma unroll
;     for (int ct = 0; ct < NCT; ++ct)
; #pragma unroll
;         for (int ks = 0; ks < 4; ++ks) { const bf16x8 kf = *(const LAS bf16x8*)(Kt + (key_row0 + 16 * ct + fr) * AT_PITCH + 64 * ks + 16 * fq);
;             s[ct] = __builtin_amdgcn_mfma_f32_16x16x32_bf16(kf, qf[ks], s[ct], 0, 0, 0); if (ks == 3 && (ct & 1)) asm volatile("" ::: "memory"); }
; }
; __device__ __forceinline__ void attnC_item(const Frame& F, const Args& a, int item) {
;     ...
;     const size_t qrow = (size_t)b * SEQ + qb * 128 + 16 * F.wave + fr;
;     const bf16_t* kbase = kv + (size_t)b * NMEM * 2048 + head * 256;
;     __syncthreads();
;     STAGE_TILE2(R0, (kbase + (size_t)i * 2048), R1, (kbase + (size_t)i * 2048 + 128));
;     bf16x8 qf[4];
;     f32x4 s[16];
; #pragma unroll
;     for (int ct = 0; ct < 16; ++ct) s[ct] = (f32x4){0.f, 0.f, 0.f, 0.f};
; #pragma unroll
;     for (int ks = 0; ks < 4; ++ks) qf[ks] = *(const bf16x8*)(proj + qrow * NIN + C_QC + head * 256 + 32 * ks + 8 * fq);
;     __syncthreads();
;     qk_accum<16>(s, R0, 0, qf, fr, fq);
.LBB0_396:
	s_ashr_i32 s34, s29, 7
	s_ashr_i32 s35, s34, 31
	s_lshl_b64 s[2:3], s[34:35], 12
	s_and_b32 s30, s13, 0xf80
	s_lshl_b64 s[34:35], s[34:35], 20
	s_add_u32 s31, s10, s34
	s_addc_u32 s33, s11, s35
	s_and_b32 s0, s28, 0x300
	s_lshl_b32 s0, s0, 1
	s_add_u32 s34, s31, s0
	s_addc_u32 s35, s33, 0
	v_lshl_add_u64 v[0:1], s[34:35], 0, v[98:99]
	v_lshl_add_u64 v[8:9], s[34:35], 0, v[100:101]
	v_lshl_add_u64 v[16:17], s[34:35], 0, v[102:103]
	v_lshl_add_u64 v[24:25], s[34:35], 0, v[104:105]
	v_lshl_add_u64 v[32:33], s[34:35], 0, v[106:107]
	v_lshl_add_u64 v[40:41], s[34:35], 0, v[108:109]
	v_lshl_add_u64 v[48:49], s[34:35], 0, v[110:111]
	v_lshl_add_u64 v[56:57], s[34:35], 0, v[112:113]
	v_lshl_add_u64 v[124:125], v[0:1], 0, v[114:115]
	v_lshl_add_u64 v[126:127], v[8:9], 0, v[114:115]
	v_lshl_add_u64 v[128:129], v[16:17], 0, v[114:115]
	v_lshl_add_u64 v[130:131], v[24:25], 0, v[114:115]
	v_lshl_add_u64 v[132:133], v[32:33], 0, v[114:115]
	v_lshl_add_u64 v[134:135], v[40:41], 0, v[114:115]
	v_lshl_add_u64 v[136:137], v[48:49], 0, v[114:115]
	v_lshl_add_u64 v[138:139], v[56:57], 0, v[114:115]
	s_waitcnt vmcnt(0)
	s_barrier
	global_load_dwordx4 v[0:3], v[124:125], off
	global_load_dwordx4 v[4:7], v[124:125], off offset:256
	global_load_dwordx4 v[8:11], v[126:127], off
	global_load_dwordx4 v[12:15], v[126:127], off offset:256
	global_load_dwordx4 v[16:19], v[128:129], off
	global_load_dwordx4 v[20:23], v[128:129], off offset:256
	global_load_dwordx4 v[24:27], v[130:131], off
	global_load_dwordx4 v[28:31], v[130:131], off offset:256
	global_load_dwordx4 v[32:35], v[132:133], off
	global_load_dwordx4 v[36:39], v[132:133], off offset:256
	global_load_dwordx4 v[40:43], v[134:135], off
	global_load_dwordx4 v[44:47], v[134:135], off offset:256
	global_load_dwordx4 v[48:51], v[136:137], off
	global_load_dwordx4 v[52:55], v[136:137], off offset:256
	global_load_dwordx4 v[56:59], v[138:139], off
	global_load_dwordx4 v[60:63], v[138:139], off offset:256
	v_add_u32_e32 v96, s30, v140
	v_lshl_add_u64 v[122:123], s[2:3], 0, v[96:97]
	s_add_i32 s29, s29, s26
	s_add_i32 s13, s13, s14
	s_add_i32 s28, s28, s94
	s_cmpk_gt_i32 s29, 0x1ff
	s_waitcnt vmcnt(15)
	ds_write_b128 v146, v[0:3]
	s_waitcnt vmcnt(14)
	ds_write_b128 v158, v[4:7]
	s_waitcnt vmcnt(13)
	ds_write_b128 v147, v[8:11]
	s_waitcnt vmcnt(12)
	ds_write_b128 v148, v[12:15]
	s_waitcnt vmcnt(11)
	ds_write_b128 v146, v[16:19] offset:17408
	s_waitcnt vmcnt(10)
	ds_write_b128 v149, v[20:23]
	s_waitcnt vmcnt(9)
	ds_write_b128 v150, v[24:27]
	s_waitcnt vmcnt(8)
	ds_write_b128 v151, v[28:31]
	s_waitcnt vmcnt(7)
	ds_write_b128 v146, v[32:35] offset:34816
	s_waitcnt vmcnt(6)
	ds_write_b128 v152, v[36:39]
	s_waitcnt vmcnt(5)
	ds_write_b128 v153, v[40:43]
	s_waitcnt vmcnt(4)
	ds_write_b128 v154, v[44:47]
	s_waitcnt vmcnt(3)
	ds_write_b128 v146, v[48:51] offset:52224
	s_waitcnt vmcnt(2)
	ds_write_b128 v155, v[52:55]
	s_waitcnt vmcnt(1)
	ds_write_b128 v156, v[56:59]
	s_waitcnt vmcnt(0)
	ds_write_b128 v157, v[60:63]
	v_mad_u64_u32 v[0:1], s[2:3], v122, s12, v[120:121]
	v_mad_i32_i24 v1, v123, s12, v1
	v_lshl_add_u64 v[0:1], v[0:1], 0, s[0:1]
	v_lshl_add_u64 v[76:77], v[0:1], 0, v[116:117]
	v_add_co_u32_e32 v78, vcc, s15, v76
	v_lshl_add_u64 v[4:5], v[76:77], 0, s[4:5]
	s_nop 0
	v_addc_co_u32_e32 v79, vcc, 0, v77, vcc
	global_load_dwordx4 v[36:39], v[78:79], off offset:3072
	global_load_dwordx4 v[8:11], v[4:5], off offset:64
	global_load_dwordx4 v[0:3], v[4:5], off offset:128
	s_nop 0
	global_load_dwordx4 v[4:7], v[4:5], off offset:192
	s_waitcnt lgkmcnt(0)
	s_barrier
	ds_read_b128 v[208:211], v141
	ds_read_b128 v[212:215], v141 offset:64
	ds_read_b128 v[216:219], v141 offset:128
	ds_read_b128 v[220:223], v141 offset:192
	ds_read_b128 v[224:227], v141 offset:4352
	ds_read_b128 v[228:231], v141 offset:4416
	ds_read_b128 v[232:235], v141 offset:4480
	ds_read_b128 v[236:239], v141 offset:4544
	ds_read_b128 v[244:247], v141 offset:13120
	ds_read_b128 v[248:251], v141 offset:8704
	ds_read_b128 v[252:255], v141 offset:8768
	s_waitcnt vmcnt(0)
	s_waitcnt lgkmcnt(10)
	v_mfma_f32_16x16x32_bf16 v[12:15], v[208:211], v[36:39], 0
	ds_read_b128 v[208:211], v141 offset:8832
	s_waitcnt lgkmcnt(10)
	v_mfma_f32_16x16x32_bf16 v[12:15], v[212:215], v[8:11], v[12:15]
	ds_read_b128 v[212:215], v141 offset:8896
	s_waitcnt lgkmcnt(10)
	v_mfma_f32_16x16x32_bf16 v[12:15], v[216:219], v[0:3], v[12:15]
	ds_read_b128 v[216:219], v141 offset:13056
	s_waitcnt lgkmcnt(10)
	v_mfma_f32_16x16x32_bf16 v[40:43], v[220:223], v[4:7], v[12:15]
	ds_read_b128 v[220:223], v141 offset:13184
	s_waitcnt lgkmcnt(10)
	v_mfma_f32_16x16x32_bf16 v[12:15], v[224:227], v[36:39], 0
	ds_read_b128 v[224:227], v141 offset:13248
	s_waitcnt lgkmcnt(10)
	v_mfma_f32_16x16x32_bf16 v[12:15], v[228:231], v[8:11], v[12:15]
	ds_read_b128 v[228:231], v141 offset:17472
	s_waitcnt lgkmcnt(10)
	v_mfma_f32_16x16x32_bf16 v[12:15], v[232:235], v[0:3], v[12:15]
	ds_read_b128 v[232:235], v141 offset:17408
	s_waitcnt lgkmcnt(10)
	v_mfma_f32_16x16x32_bf16 v[28:31], v[236:239], v[4:7], v[12:15]
	ds_read_b128 v[236:239], v141 offset:21824
	s_waitcnt lgkmcnt(9)
	v_mfma_f32_16x16x32_bf16 v[12:15], v[248:251], v[36:39], 0
	ds_read_b128 v[248:251], v141 offset:17536
	s_waitcnt lgkmcnt(9)
	v_mfma_f32_16x16x32_bf16 v[12:15], v[252:255], v[8:11], v[12:15]
	ds_read_b128 v[252:255], v141 offset:17600
	s_waitcnt lgkmcnt(9)
	v_mfma_f32_16x16x32_bf16 v[12:15], v[208:211], v[0:3], v[12:15]
	ds_read_b128 v[208:211], v141 offset:21760
	s_waitcnt lgkmcnt(9)
	v_mfma_f32_16x16x32_bf16 v[12:15], v[212:215], v[4:7], v[12:15]
	ds_read_b128 v[212:215], v141 offset:21888
	s_waitcnt lgkmcnt(9)
; #define LAS __attribute__((address_space(3)))
; template <int NCT>
; __device__ __forceinline__ void qk_accum(f32x4 (&s)[NCT], const LAS unsigned char* Kt, int key_row0, const bf16x8 (&qf)[4], int fr, int fq) {
; #pragma unroll
;     for (int ct = 0; ct < NCT; ++ct)
; #pragma unroll
;         for (int ks = 0; ks < 4; ++ks) { const bf16x8 kf = *(const LAS bf16x8*)(Kt + (key_row0 + 16 * ct + fr) * AT_PITCH + 64 * ks + 16 * fq);
;             s[ct] = __builtin_amdgcn_mfma_f32_16x16x32_bf16(kf, qf[ks], s[ct], 0, 0, 0); if (ks == 3 && (ct & 1)) asm volatile("" ::: "memory"); }
; }
	v_mfma_f32_16x16x32_bf16 v[16:19], v[216:219], v[36:39], 0
	ds_read_b128 v[216:219], v141 offset:21952
	s_waitcnt lgkmcnt(15)
	v_mfma_f32_16x16x32_bf16 v[16:19], v[244:247], v[8:11], v[16:19]
	ds_read_b128 v[244:247], v141 offset:30528
	s_waitcnt lgkmcnt(10)
	v_mfma_f32_16x16x32_bf16 v[16:19], v[220:223], v[0:3], v[16:19]
	ds_read_b128 v[220:223], v141 offset:26112
	s_waitcnt lgkmcnt(10)
	v_mfma_f32_16x16x32_bf16 v[20:23], v[224:227], v[4:7], v[16:19]
	ds_read_b128 v[224:227], v141 offset:26176
	s_waitcnt lgkmcnt(9)
	v_mfma_f32_16x16x32_bf16 v[16:19], v[232:235], v[36:39], 0
	ds_read_b128 v[232:235], v141 offset:26240
	s_waitcnt lgkmcnt(11)
	v_mfma_f32_16x16x32_bf16 v[16:19], v[228:231], v[8:11], v[16:19]
	ds_read_b128 v[228:231], v141 offset:26304
	s_waitcnt lgkmcnt(9)
	v_mfma_f32_16x16x32_bf16 v[16:19], v[248:251], v[0:3], v[16:19]
	ds_read_b128 v[248:251], v141 offset:30464
	s_waitcnt lgkmcnt(9)
	v_mfma_f32_16x16x32_bf16 v[16:19], v[252:255], v[4:7], v[16:19]
	ds_read_b128 v[252:255], v141 offset:30592
	s_waitcnt lgkmcnt(9)
	v_mfma_f32_16x16x32_bf16 v[24:27], v[208:211], v[36:39], 0
	ds_read_b128 v[208:211], v141 offset:30656
	s_waitcnt lgkmcnt(13)
	v_mfma_f32_16x16x32_bf16 v[24:27], v[236:239], v[8:11], v[24:27]
	ds_read_b128 v[236:239], v141 offset:39232
	s_waitcnt lgkmcnt(10)
	v_mfma_f32_16x16x32_bf16 v[24:27], v[212:215], v[0:3], v[24:27]
	ds_read_b128 v[212:215], v141 offset:34816
	s_waitcnt lgkmcnt(10)
	v_mfma_f32_16x16x32_bf16 v[48:51], v[216:219], v[4:7], v[24:27]
	ds_read_b128 v[216:219], v141 offset:34880
	s_waitcnt lgkmcnt(9)
	v_mfma_f32_16x16x32_bf16 v[24:27], v[220:223], v[36:39], 0
	ds_read_b128 v[220:223], v141 offset:34944
	s_waitcnt lgkmcnt(9)
	v_mfma_f32_16x16x32_bf16 v[24:27], v[224:227], v[8:11], v[24:27]
	ds_read_b128 v[224:227], v141 offset:35008
	s_waitcnt lgkmcnt(9)
	v_mfma_f32_16x16x32_bf16 v[24:27], v[232:235], v[0:3], v[24:27]
	ds_read_b128 v[232:235], v141 offset:39168
	s_waitcnt lgkmcnt(9)
	v_mfma_f32_16x16x32_bf16 v[24:27], v[228:231], v[4:7], v[24:27]
	ds_read_b128 v[228:231], v141 offset:39296
	s_waitcnt lgkmcnt(9)
	v_mfma_f32_16x16x32_bf16 v[32:35], v[248:251], v[36:39], 0
	ds_read_b128 v[248:251], v141 offset:39360
	s_waitcnt lgkmcnt(15)
	v_mfma_f32_16x16x32_bf16 v[32:35], v[244:247], v[8:11], v[32:35]
	ds_read_b128 v[244:247], v141 offset:47936
	s_waitcnt lgkmcnt(10)
	v_mfma_f32_16x16x32_bf16 v[32:35], v[252:255], v[0:3], v[32:35]
	ds_read_b128 v[252:255], v141 offset:43520
	s_waitcnt lgkmcnt(10)
	v_mfma_f32_16x16x32_bf16 v[60:63], v[208:211], v[4:7], v[32:35]
	ds_read_b128 v[208:211], v141 offset:43584
	s_waitcnt lgkmcnt(9)
	v_mfma_f32_16x16x32_bf16 v[32:35], v[212:215], v[36:39], 0
	ds_read_b128 v[212:215], v141 offset:43648
	s_waitcnt lgkmcnt(9)
	v_mfma_f32_16x16x32_bf16 v[32:35], v[216:219], v[8:11], v[32:35]
	ds_read_b128 v[216:219], v141 offset:43712
	s_waitcnt lgkmcnt(9)
	v_mfma_f32_16x16x32_bf16 v[32:35], v[220:223], v[0:3], v[32:35]
	ds_read_b128 v[220:223], v141 offset:47872
	s_waitcnt lgkmcnt(9)
	v_mfma_f32_16x16x32_bf16 v[32:35], v[224:227], v[4:7], v[32:35]
	ds_read_b128 v[224:227], v141 offset:48000
	s_waitcnt lgkmcnt(9)
	v_mfma_f32_16x16x32_bf16 v[44:47], v[232:235], v[36:39], 0
	ds_read_b128 v[232:235], v141 offset:48064
	s_waitcnt lgkmcnt(15)
	v_mfma_f32_16x16x32_bf16 v[44:47], v[236:239], v[8:11], v[44:47]
	ds_read_b128 v[236:239], v141 offset:56640
	s_waitcnt lgkmcnt(10)
	v_mfma_f32_16x16x32_bf16 v[44:47], v[228:231], v[0:3], v[44:47]
	ds_read_b128 v[228:231], v141 offset:52224
	s_waitcnt lgkmcnt(10)
	v_mfma_f32_16x16x32_bf16 v[56:59], v[248:251], v[4:7], v[44:47]
	ds_read_b128 v[248:251], v141 offset:52288
	s_waitcnt lgkmcnt(9)
	v_mfma_f32_16x16x32_bf16 v[44:47], v[252:255], v[36:39], 0
	ds_read_b128 v[252:255], v141 offset:52352
	s_waitcnt lgkmcnt(9)
	v_mfma_f32_16x16x32_bf16 v[44:47], v[208:211], v[8:11], v[44:47]
	ds_read_b128 v[208:211], v141 offset:52416
	s_waitcnt lgkmcnt(9)
	v_mfma_f32_16x16x32_bf16 v[44:47], v[212:215], v[0:3], v[44:47]
	ds_read_b128 v[212:215], v141 offset:56576
	s_waitcnt lgkmcnt(9)
	v_mfma_f32_16x16x32_bf16 v[44:47], v[216:219], v[4:7], v[44:47]
	ds_read_b128 v[216:219], v141 offset:56704
	s_waitcnt lgkmcnt(9)
	v_mfma_f32_16x16x32_bf16 v[52:55], v[220:223], v[36:39], 0
	ds_read_b128 v[220:223], v141 offset:56768
	s_waitcnt lgkmcnt(15)
	v_mfma_f32_16x16x32_bf16 v[52:55], v[244:247], v[8:11], v[52:55]
	ds_read_b128 v[244:247], v141 offset:60992
	s_waitcnt lgkmcnt(10)
	v_mfma_f32_16x16x32_bf16 v[52:55], v[224:227], v[0:3], v[52:55]
	ds_read_b128 v[224:227], v141 offset:60928
	s_waitcnt lgkmcnt(10)
	v_mfma_f32_16x16x32_bf16 v[68:71], v[232:235], v[4:7], v[52:55]
	ds_read_b128 v[232:235], v141 offset:61056
	s_waitcnt lgkmcnt(9)
	v_mfma_f32_16x16x32_bf16 v[52:55], v[228:231], v[36:39], 0
	ds_read_b128 v[228:231], v141 offset:61120
	s_waitcnt lgkmcnt(9)
	v_mfma_f32_16x16x32_bf16 v[52:55], v[248:251], v[8:11], v[52:55]
	ds_read_b128 v[248:251], v141 offset:65280
	s_waitcnt lgkmcnt(9)
	v_mfma_f32_16x16x32_bf16 v[52:55], v[252:255], v[0:3], v[52:55]
	ds_read_b128 v[252:255], v141 offset:65344
	s_waitcnt lgkmcnt(9)
	v_mfma_f32_16x16x32_bf16 v[52:55], v[208:211], v[4:7], v[52:55]
	ds_read_b128 v[208:211], v141 offset:65408
	s_waitcnt lgkmcnt(9)
	v_mfma_f32_16x16x32_bf16 v[64:67], v[212:215], v[36:39], 0
	ds_read_b128 v[212:215], v141 offset:65472
	s_waitcnt lgkmcnt(15)
	v_mfma_f32_16x16x32_bf16 v[64:67], v[236:239], v[8:11], v[64:67]
	s_waitcnt lgkmcnt(9)
	v_mfma_f32_16x16x32_bf16 v[64:67], v[216:219], v[0:3], v[64:67]
	s_waitcnt lgkmcnt(8)
	v_mfma_f32_16x16x32_bf16 v[72:75], v[220:223], v[4:7], v[64:67]
	s_waitcnt lgkmcnt(6)
; #define LAS __attribute__((address_space(3)))
; template <int NCT>
; __device__ __forceinline__ void qk_accum(f32x4 (&s)[NCT], const LAS unsigned char* Kt, int key_row0, const bf16x8 (&qf)[4], int fr, int fq) {
; #pragma unroll
;     for (int ct = 0; ct < NCT; ++ct)
; #pragma unroll
;         for (int ks = 0; ks < 4; ++ks) { const bf16x8 kf = *(const LAS bf16x8*)(Kt + (key_row0 + 16 * ct + fr) * AT_PITCH + 64 * ks + 16 * fq);
;             s[ct] = __builtin_amdgcn_mfma_f32_16x16x32_bf16(kf, qf[ks], s[ct], 0, 0, 0); if (ks == 3 && (ct & 1)) asm volatile("" ::: "memory"); }
; }
; __device__ __forceinline__ void attnC_item(const Frame& F, const Args& a, int item) {
;     ...
;     for (int ks = 0; ks < 4; ++ks) qf[ks] = *(const bf16x8*)(proj + qrow * NIN + C_QC + head * 256 + 128 + 32 * ks + 8 * fq);
;     qk_accum<16>(s, R1, 0, qf, fr, fq);
	v_mfma_f32_16x16x32_bf16 v[64:67], v[224:227], v[36:39], 0
	s_waitcnt lgkmcnt(7)
	v_mfma_f32_16x16x32_bf16 v[64:67], v[244:247], v[8:11], v[64:67]
	s_waitcnt lgkmcnt(5)
	v_mfma_f32_16x16x32_bf16 v[64:67], v[232:235], v[0:3], v[64:67]
	s_waitcnt lgkmcnt(4)
	v_mfma_f32_16x16x32_bf16 v[64:67], v[228:231], v[4:7], v[64:67]
	s_waitcnt lgkmcnt(3)
	v_mfma_f32_16x16x32_bf16 v[36:39], v[248:251], v[36:39], 0
	s_waitcnt lgkmcnt(2)
	v_mfma_f32_16x16x32_bf16 v[8:11], v[252:255], v[8:11], v[36:39]
	s_waitcnt lgkmcnt(1)
	v_mfma_f32_16x16x32_bf16 v[0:3], v[208:211], v[0:3], v[8:11]
	s_waitcnt lgkmcnt(0)
	v_mfma_f32_16x16x32_bf16 v[88:91], v[212:215], v[4:7], v[0:3]
	s_nop 2
	v_lshl_add_u64 v[0:1], v[76:77], 0, s[6:7]
	global_load_dwordx4 v[92:95], v[78:79], off offset:3328
	global_load_dwordx4 v[84:87], v[0:1], off offset:64
	global_load_dwordx4 v[80:83], v[0:1], off offset:128
	s_nop 0
	global_load_dwordx4 v[76:79], v[0:1], off offset:192
	ds_read_b128 v[208:211], v142
	ds_read_b128 v[212:215], v142 offset:64
	ds_read_b128 v[216:219], v142 offset:4416
	ds_read_b128 v[220:223], v142 offset:128
	ds_read_b128 v[224:227], v142 offset:192
	ds_read_b128 v[228:231], v142 offset:4352
	ds_read_b128 v[232:235], v142 offset:4480
	ds_read_b128 v[236:239], v142 offset:4544
	ds_read_b128 v[244:247], v142 offset:8704
	ds_read_b128 v[248:251], v142 offset:8768
	ds_read_b128 v[252:255], v142 offset:8832
	s_waitcnt vmcnt(0)
	s_waitcnt lgkmcnt(10)
	v_mfma_f32_16x16x32_bf16 v[0:3], v[208:211], v[92:95], v[40:43]
	ds_read_b128 v[208:211], v142 offset:8896
	s_waitcnt lgkmcnt(10)
	v_mfma_f32_16x16x32_bf16 v[0:3], v[212:215], v[84:87], v[0:3]
	ds_read_b128 v[212:215], v142 offset:13056
	s_waitcnt lgkmcnt(9)
	v_mfma_f32_16x16x32_bf16 v[0:3], v[220:223], v[80:83], v[0:3]
	ds_read_b128 v[220:223], v142 offset:13120
	s_waitcnt lgkmcnt(9)
	v_mfma_f32_16x16x32_bf16 v[0:3], v[224:227], v[76:79], v[0:3]
	ds_read_b128 v[224:227], v142 offset:13184
	s_waitcnt lgkmcnt(9)
	v_mfma_f32_16x16x32_bf16 v[4:7], v[228:231], v[92:95], v[28:31]
	ds_read_b128 v[228:231], v142 offset:13248
	s_waitcnt lgkmcnt(13)
	v_mfma_f32_16x16x32_bf16 v[4:7], v[216:219], v[84:87], v[4:7]
	ds_read_b128 v[216:219], v142 offset:21824
	s_waitcnt lgkmcnt(10)
	v_mfma_f32_16x16x32_bf16 v[4:7], v[232:235], v[80:83], v[4:7]
	ds_read_b128 v[232:235], v142 offset:17408
	s_waitcnt lgkmcnt(10)
	v_mfma_f32_16x16x32_bf16 v[4:7], v[236:239], v[76:79], v[4:7]
	ds_read_b128 v[236:239], v142 offset:17472
	s_waitcnt lgkmcnt(10)
	v_mfma_f32_16x16x32_bf16 v[8:11], v[244:247], v[92:95], v[12:15]
	ds_read_b128 v[244:247], v142 offset:17536
	s_waitcnt lgkmcnt(10)
	v_mfma_f32_16x16x32_bf16 v[8:11], v[248:251], v[84:87], v[8:11]
	ds_read_b128 v[248:251], v142 offset:17600
	s_waitcnt lgkmcnt(10)
	v_mfma_f32_16x16x32_bf16 v[8:11], v[252:255], v[80:83], v[8:11]
	ds_read_b128 v[252:255], v142 offset:21760
	s_waitcnt lgkmcnt(10)
	v_mfma_f32_16x16x32_bf16 v[8:11], v[208:211], v[76:79], v[8:11]
	ds_read_b128 v[208:211], v142 offset:21888
	s_waitcnt lgkmcnt(10)
	v_mfma_f32_16x16x32_bf16 v[12:15], v[212:215], v[92:95], v[20:23]
	ds_read_b128 v[212:215], v142 offset:21952
	s_waitcnt lgkmcnt(10)
	v_mfma_f32_16x16x32_bf16 v[12:15], v[220:223], v[84:87], v[12:15]
	ds_read_b128 v[220:223], v142 offset:30528
	s_waitcnt lgkmcnt(10)
	v_mfma_f32_16x16x32_bf16 v[12:15], v[224:227], v[80:83], v[12:15]
	ds_read_b128 v[224:227], v142 offset:26112
	s_waitcnt lgkmcnt(10)
	v_mfma_f32_16x16x32_bf16 v[12:15], v[228:231], v[76:79], v[12:15]
	ds_read_b128 v[228:231], v142 offset:26176
	s_waitcnt lgkmcnt(9)
	v_mfma_f32_16x16x32_bf16 v[16:19], v[232:235], v[92:95], v[16:19]
	ds_read_b128 v[232:235], v142 offset:26240
	s_waitcnt lgkmcnt(9)
	v_mfma_f32_16x16x32_bf16 v[16:19], v[236:239], v[84:87], v[16:19]
	ds_read_b128 v[236:239], v142 offset:26304
	s_waitcnt lgkmcnt(9)
	v_mfma_f32_16x16x32_bf16 v[16:19], v[244:247], v[80:83], v[16:19]
	ds_read_b128 v[244:247], v142 offset:30464
	s_waitcnt lgkmcnt(9)
	v_mfma_f32_16x16x32_bf16 v[16:19], v[248:251], v[76:79], v[16:19]
	ds_read_b128 v[248:251], v142 offset:30592
	s_waitcnt lgkmcnt(9)
	v_mfma_f32_16x16x32_bf16 v[20:23], v[252:255], v[92:95], v[48:51]
	ds_read_b128 v[252:255], v142 offset:30656
	s_waitcnt lgkmcnt(15)
	v_mfma_f32_16x16x32_bf16 v[20:23], v[216:219], v[84:87], v[20:23]
	ds_read_b128 v[216:219], v142 offset:39232
	s_waitcnt lgkmcnt(10)
	v_mfma_f32_16x16x32_bf16 v[20:23], v[208:211], v[80:83], v[20:23]
	ds_read_b128 v[208:211], v142 offset:34816
	s_waitcnt lgkmcnt(10)
	v_mfma_f32_16x16x32_bf16 v[20:23], v[212:215], v[76:79], v[20:23]
	ds_read_b128 v[212:215], v142 offset:34880
	s_waitcnt lgkmcnt(9)
	v_mfma_f32_16x16x32_bf16 v[24:27], v[224:227], v[92:95], v[24:27]
	ds_read_b128 v[224:227], v142 offset:34944
	s_waitcnt lgkmcnt(9)
	v_mfma_f32_16x16x32_bf16 v[24:27], v[228:231], v[84:87], v[24:27]
	ds_read_b128 v[228:231], v142 offset:35008
	s_waitcnt lgkmcnt(9)
	v_mfma_f32_16x16x32_bf16 v[24:27], v[232:235], v[80:83], v[24:27]
	ds_read_b128 v[232:235], v142 offset:39168
	s_waitcnt lgkmcnt(9)
	v_mfma_f32_16x16x32_bf16 v[24:27], v[236:239], v[76:79], v[24:27]
	ds_read_b128 v[236:239], v142 offset:39296
	s_waitcnt lgkmcnt(9)
	v_mfma_f32_16x16x32_bf16 v[28:31], v[244:247], v[92:95], v[60:63]
	ds_read_b128 v[244:247], v142 offset:39360
	s_waitcnt lgkmcnt(15)
	v_mfma_f32_16x16x32_bf16 v[28:31], v[220:223], v[84:87], v[28:31]
	ds_read_b128 v[220:223], v142 offset:47936
	s_waitcnt lgkmcnt(10)
	v_mfma_f32_16x16x32_bf16 v[28:31], v[248:251], v[80:83], v[28:31]
	ds_read_b128 v[248:251], v142 offset:43520
	s_waitcnt lgkmcnt(10)
	v_mfma_f32_16x16x32_bf16 v[28:31], v[252:255], v[76:79], v[28:31]
	ds_read_b128 v[252:255], v142 offset:43584
	s_waitcnt lgkmcnt(9)
; #define LAS __attribute__((address_space(3)))
; template <int NCT>
; __device__ __forceinline__ void qk_accum(f32x4 (&s)[NCT], const LAS unsigned char* Kt, int key_row0, const bf16x8 (&qf)[4], int fr, int fq) {
; #pragma unroll
;     for (int ct = 0; ct < NCT; ++ct)
; #pragma unroll
;         for (int ks = 0; ks < 4; ++ks) { const bf16x8 kf = *(const LAS bf16x8*)(Kt + (key_row0 + 16 * ct + fr) * AT_PITCH + 64 * ks + 16 * fq);
;             s[ct] = __builtin_amdgcn_mfma_f32_16x16x32_bf16(kf, qf[ks], s[ct], 0, 0, 0); if (ks == 3 && (ct & 1)) asm volatile("" ::: "memory"); }
; }
; __device__ __forceinline__ void attnC_item(const Frame& F, const Args& a, int item) {
;     ...
;     float mx = -3.0e38f;
; #pragma unroll
;     for (int ct = 0; ct < 16; ++ct)
; #pragma unroll
;         for (int j = 0; j < 4; ++j) { const float l = s[ct][j] * 0.0625f; s[ct][j] = l; mx = fmaxf(mx, l); }
	v_mfma_f32_16x16x32_bf16 v[32:35], v[208:211], v[92:95], v[32:35]
	ds_read_b128 v[208:211], v142 offset:43648
	s_waitcnt lgkmcnt(9)
	v_mfma_f32_16x16x32_bf16 v[32:35], v[212:215], v[84:87], v[32:35]
	ds_read_b128 v[212:215], v142 offset:43712
	s_waitcnt lgkmcnt(9)
	v_mfma_f32_16x16x32_bf16 v[32:35], v[224:227], v[80:83], v[32:35]
	ds_read_b128 v[224:227], v142 offset:47872
	s_waitcnt lgkmcnt(9)
	v_mfma_f32_16x16x32_bf16 v[32:35], v[228:231], v[76:79], v[32:35]
	ds_read_b128 v[228:231], v142 offset:48000
	s_waitcnt lgkmcnt(9)
	v_mfma_f32_16x16x32_bf16 v[36:39], v[232:235], v[92:95], v[56:59]
	ds_read_b128 v[232:235], v142 offset:48064
	s_waitcnt lgkmcnt(15)
	v_mfma_f32_16x16x32_bf16 v[36:39], v[216:219], v[84:87], v[36:39]
	ds_read_b128 v[216:219], v142 offset:56640
	s_waitcnt lgkmcnt(10)
	v_mfma_f32_16x16x32_bf16 v[36:39], v[236:239], v[80:83], v[36:39]
	ds_read_b128 v[236:239], v142 offset:52224
	s_waitcnt lgkmcnt(10)
	v_mfma_f32_16x16x32_bf16 v[40:43], v[244:247], v[76:79], v[36:39]
	ds_read_b128 v[244:247], v142 offset:52288
	s_waitcnt lgkmcnt(9)
	v_mfma_f32_16x16x32_bf16 v[36:39], v[248:251], v[92:95], v[44:47]
	ds_read_b128 v[248:251], v142 offset:52352
	s_waitcnt lgkmcnt(9)
	v_mfma_f32_16x16x32_bf16 v[36:39], v[252:255], v[84:87], v[36:39]
	ds_read_b128 v[252:255], v142 offset:52416
	s_waitcnt lgkmcnt(9)
	v_mfma_f32_16x16x32_bf16 v[36:39], v[208:211], v[80:83], v[36:39]
	ds_read_b128 v[208:211], v142 offset:56576
	s_waitcnt lgkmcnt(9)
	v_mfma_f32_16x16x32_bf16 v[36:39], v[212:215], v[76:79], v[36:39]
	ds_read_b128 v[212:215], v142 offset:56704
	s_waitcnt lgkmcnt(9)
	v_mfma_f32_16x16x32_bf16 v[44:47], v[224:227], v[92:95], v[68:71]
	ds_read_b128 v[224:227], v142 offset:56768
	s_waitcnt lgkmcnt(15)
	v_mfma_f32_16x16x32_bf16 v[44:47], v[220:223], v[84:87], v[44:47]
	ds_read_b128 v[220:223], v142 offset:60992
	s_waitcnt lgkmcnt(10)
	v_mfma_f32_16x16x32_bf16 v[44:47], v[228:231], v[80:83], v[44:47]
	ds_read_b128 v[228:231], v142 offset:60928
	s_waitcnt lgkmcnt(10)
	v_mfma_f32_16x16x32_bf16 v[48:51], v[232:235], v[76:79], v[44:47]
	ds_read_b128 v[232:235], v142 offset:65344
	s_waitcnt lgkmcnt(9)
	v_mfma_f32_16x16x32_bf16 v[44:47], v[236:239], v[92:95], v[52:55]
	ds_read_b128 v[236:239], v142 offset:61056
	s_waitcnt lgkmcnt(9)
	v_mfma_f32_16x16x32_bf16 v[44:47], v[244:247], v[84:87], v[44:47]
	ds_read_b128 v[244:247], v142 offset:61120
	s_waitcnt lgkmcnt(9)
	v_mfma_f32_16x16x32_bf16 v[44:47], v[248:251], v[80:83], v[44:47]
	ds_read_b128 v[248:251], v142 offset:65280
	s_waitcnt lgkmcnt(9)
	v_mfma_f32_16x16x32_bf16 v[44:47], v[252:255], v[76:79], v[44:47]
	ds_read_b128 v[252:255], v142 offset:65408
	s_waitcnt lgkmcnt(9)
	v_mfma_f32_16x16x32_bf16 v[52:55], v[208:211], v[92:95], v[72:75]
	ds_read_b128 v[208:211], v142 offset:65472
	s_waitcnt lgkmcnt(15)
	v_mfma_f32_16x16x32_bf16 v[52:55], v[216:219], v[84:87], v[52:55]
	s_waitcnt lgkmcnt(9)
	v_mfma_f32_16x16x32_bf16 v[52:55], v[212:215], v[80:83], v[52:55]
	s_waitcnt lgkmcnt(8)
	v_mfma_f32_16x16x32_bf16 v[56:59], v[224:227], v[76:79], v[52:55]
	s_waitcnt lgkmcnt(6)
	v_mfma_f32_16x16x32_bf16 v[52:55], v[228:231], v[92:95], v[64:67]
	s_waitcnt lgkmcnt(7)
	v_mfma_f32_16x16x32_bf16 v[52:55], v[220:223], v[84:87], v[52:55]
	s_waitcnt lgkmcnt(4)
	v_mfma_f32_16x16x32_bf16 v[52:55], v[236:239], v[80:83], v[52:55]
	s_waitcnt lgkmcnt(3)
	v_mfma_f32_16x16x32_bf16 v[52:55], v[244:247], v[76:79], v[52:55]
	s_waitcnt lgkmcnt(2)
	v_mfma_f32_16x16x32_bf16 v[60:63], v[248:251], v[92:95], v[88:91]
	s_waitcnt lgkmcnt(5)
	v_mfma_f32_16x16x32_bf16 v[60:63], v[232:235], v[84:87], v[60:63]
	s_waitcnt lgkmcnt(1)
	v_mfma_f32_16x16x32_bf16 v[60:63], v[252:255], v[80:83], v[60:63]
	s_waitcnt lgkmcnt(0)
	v_mfma_f32_16x16x32_bf16 v[60:63], v[208:211], v[76:79], v[60:63]
	v_mul_f32_e32 v64, 0x3d800000, v0
	v_mul_f32_e32 v65, 0x3d800000, v1
	v_max3_f32 v64, v64, s17, v65
	v_mul_f32_e32 v65, 0x3d800000, v2
	v_mul_f32_e32 v66, 0x3d800000, v3
	v_max3_f32 v64, v64, v65, v66
	v_mul_f32_e32 v65, 0x3d800000, v4
	v_mul_f32_e32 v66, 0x3d800000, v5
	v_max3_f32 v64, v64, v65, v66
	v_mul_f32_e32 v65, 0x3d800000, v6
	v_mul_f32_e32 v66, 0x3d800000, v7
	v_max3_f32 v64, v64, v65, v66
	v_mul_f32_e32 v65, 0x3d800000, v8
	v_mul_f32_e32 v66, 0x3d800000, v9
	v_max3_f32 v64, v64, v65, v66
	v_mul_f32_e32 v65, 0x3d800000, v10
	v_mul_f32_e32 v66, 0x3d800000, v11
	v_max3_f32 v64, v64, v65, v66
	v_mul_f32_e32 v65, 0x3d800000, v12
	v_mul_f32_e32 v66, 0x3d800000, v13
	v_max3_f32 v64, v64, v65, v66
	v_mul_f32_e32 v65, 0x3d800000, v14
	v_mul_f32_e32 v66, 0x3d800000, v15
	v_max3_f32 v64, v64, v65, v66
	v_mul_f32_e32 v65, 0x3d800000, v16
	v_mul_f32_e32 v66, 0x3d800000, v17
	v_max3_f32 v64, v64, v65, v66
	v_mul_f32_e32 v65, 0x3d800000, v18
	v_mul_f32_e32 v66, 0x3d800000, v19
	v_max3_f32 v64, v64, v65, v66
	v_mul_f32_e32 v65, 0x3d800000, v20
	v_mul_f32_e32 v66, 0x3d800000, v21
	v_max3_f32 v64, v64, v65, v66
	v_mul_f32_e32 v65, 0x3d800000, v22
	v_mul_f32_e32 v66, 0x3d800000, v23
	v_max3_f32 v64, v64, v65, v66
	v_mul_f32_e32 v65, 0x3d800000, v24
	v_mul_f32_e32 v66, 0x3d800000, v25
	v_max3_f32 v64, v64, v65, v66
	v_mul_f32_e32 v65, 0x3d800000, v26
	v_mul_f32_e32 v66, 0x3d800000, v27
	v_max3_f32 v64, v64, v65, v66
	v_mul_f32_e32 v65, 0x3d800000, v28
	v_mul_f32_e32 v66, 0x3d800000, v29
	v_max3_f32 v64, v64, v65, v66
	v_mul_f32_e32 v65, 0x3d800000, v30
	v_mul_f32_e32 v66, 0x3d800000, v31
	v_max3_f32 v64, v64, v65, v66
	v_mul_f32_e32 v65, 0x3d800000, v32
	v_mul_f32_e32 v66, 0x3d800000, v33
	v_max3_f32 v64, v64, v65, v66
	v_mul_f32_e32 v65, 0x3d800000, v34
	v_mul_f32_e32 v66, 0x3d800000, v35
	v_max3_f32 v64, v64, v65, v66
	v_mul_f32_e32 v65, 0x3d800000, v40
; __device__ __forceinline__ void attnC_item(const Frame& F, const Args& a, int item) {
;     ...
;     for (int ct = 0; ct < 16; ++ct)
; #pragma unroll
;         for (int j = 0; j < 4; ++j) { const float l = s[ct][j] * 0.0625f; s[ct][j] = l; mx = fmaxf(mx, l); }
;     mx = fmaxf(mx, __shfl_xor(mx, 16)); mx = fmaxf(mx, __shfl_xor(mx, 32));
;     float sum = 0.f;
; #pragma unroll
;     for (int ct = 0; ct < 16; ++ct)
; #pragma unroll
;         for (int j = 0; j < 4; ++j) { const float p = __expf(s[ct][j] - mx); s[ct][j] = p; sum += p; }
	v_mul_f32_e32 v66, 0x3d800000, v41
	v_max3_f32 v64, v64, v65, v66
	v_mul_f32_e32 v65, 0x3d800000, v42
	v_mul_f32_e32 v66, 0x3d800000, v43
	v_max3_f32 v64, v64, v65, v66
	v_mul_f32_e32 v65, 0x3d800000, v36
	v_mul_f32_e32 v66, 0x3d800000, v37
	v_max3_f32 v64, v64, v65, v66
	v_mul_f32_e32 v65, 0x3d800000, v38
	v_mul_f32_e32 v66, 0x3d800000, v39
	v_max3_f32 v64, v64, v65, v66
	v_mul_f32_e32 v65, 0x3d800000, v48
	v_mul_f32_e32 v66, 0x3d800000, v49
	v_max3_f32 v64, v64, v65, v66
	v_mul_f32_e32 v65, 0x3d800000, v50
	v_mul_f32_e32 v66, 0x3d800000, v51
	v_max3_f32 v64, v64, v65, v66
	v_mul_f32_e32 v65, 0x3d800000, v44
	v_mul_f32_e32 v66, 0x3d800000, v45
	v_max3_f32 v64, v64, v65, v66
	v_mul_f32_e32 v65, 0x3d800000, v46
	v_mul_f32_e32 v66, 0x3d800000, v47
	v_max3_f32 v64, v64, v65, v66
	v_mul_f32_e32 v65, 0x3d800000, v56
	v_mul_f32_e32 v66, 0x3d800000, v57
	v_max3_f32 v64, v64, v65, v66
	v_mul_f32_e32 v65, 0x3d800000, v58
	v_mul_f32_e32 v66, 0x3d800000, v59
	v_max3_f32 v64, v64, v65, v66
	v_mul_f32_e32 v65, 0x3d800000, v52
	v_mul_f32_e32 v66, 0x3d800000, v53
	v_max3_f32 v64, v64, v65, v66
	v_mul_f32_e32 v65, 0x3d800000, v54
	v_mul_f32_e32 v66, 0x3d800000, v55
	v_max3_f32 v64, v64, v65, v66
	v_mul_f32_e32 v65, 0x3d800000, v60
	v_mul_f32_e32 v66, 0x3d800000, v61
	v_max3_f32 v64, v64, v65, v66
	v_mul_f32_e32 v65, 0x3d800000, v62
	v_mul_f32_e32 v66, 0x3d800000, v63
	v_max3_f32 v64, v64, v65, v66
	v_and_b32_e32 v65, 64, v159
	v_add_u32_e32 v65, 64, v65
	v_cmp_lt_i32_e32 vcc, v160, v65
	s_nop 1
	v_cndmask_b32_e32 v66, v159, v160, vcc
	v_lshlrev_b32_e32 v66, 2, v66
	ds_bpermute_b32 v67, v66, v64
	s_waitcnt lgkmcnt(0)
	v_max_f32_e32 v67, v67, v67
	v_max_f32_e32 v64, v64, v67
	v_xor_b32_e32 v67, 32, v159
	v_cmp_lt_i32_e32 vcc, v67, v65
	s_nop 1
	v_cndmask_b32_e32 v65, v159, v67, vcc
	v_lshlrev_b32_e32 v65, 2, v65
	ds_bpermute_b32 v67, v65, v64
	s_waitcnt lgkmcnt(0)
	v_max_f32_e32 v67, v67, v67
	v_max_f32_e32 v64, v64, v67
	v_fma_f32 v0, v0, s16, -v64
	v_mul_f32_e32 v0, 0x3fb8aa3b, v0
	v_fma_f32 v1, v1, s16, -v64
	v_exp_f32_e32 v0, v0
	v_mul_f32_e32 v1, 0x3fb8aa3b, v1
	v_fma_f32 v2, v2, s16, -v64
	v_exp_f32_e32 v1, v1
	v_mul_f32_e32 v2, 0x3fb8aa3b, v2
	v_fma_f32 v3, v3, s16, -v64
	v_exp_f32_e32 v2, v2
	v_mul_f32_e32 v3, 0x3fb8aa3b, v3
	v_fma_f32 v4, v4, s16, -v64
	v_exp_f32_e32 v3, v3
	v_mul_f32_e32 v4, 0x3fb8aa3b, v4
	v_fma_f32 v5, v5, s16, -v64
	v_add_f32_e32 v67, 0, v0
	v_exp_f32_e32 v4, v4
	v_mul_f32_e32 v5, 0x3fb8aa3b, v5
	v_fma_f32 v6, v6, s16, -v64
	v_add_f32_e32 v67, v1, v67
	v_exp_f32_e32 v5, v5
	v_mul_f32_e32 v6, 0x3fb8aa3b, v6
	v_fma_f32 v7, v7, s16, -v64
	v_add_f32_e32 v67, v2, v67
	v_exp_f32_e32 v6, v6
	v_mul_f32_e32 v7, 0x3fb8aa3b, v7
	v_fma_f32 v8, v8, s16, -v64
	v_add_f32_e32 v67, v3, v67
	v_exp_f32_e32 v7, v7
	v_mul_f32_e32 v8, 0x3fb8aa3b, v8
	v_fma_f32 v9, v9, s16, -v64
	v_add_f32_e32 v67, v4, v67
	v_exp_f32_e32 v8, v8
	v_mul_f32_e32 v9, 0x3fb8aa3b, v9
	v_fma_f32 v10, v10, s16, -v64
	v_add_f32_e32 v67, v5, v67
	v_exp_f32_e32 v9, v9
	v_mul_f32_e32 v10, 0x3fb8aa3b, v10
	v_fma_f32 v11, v11, s16, -v64
	v_add_f32_e32 v67, v6, v67
	v_exp_f32_e32 v10, v10
	v_mul_f32_e32 v11, 0x3fb8aa3b, v11
	v_fma_f32 v12, v12, s16, -v64
	v_add_f32_e32 v67, v7, v67
	v_exp_f32_e32 v11, v11
	v_mul_f32_e32 v12, 0x3fb8aa3b, v12
	v_fma_f32 v13, v13, s16, -v64
	v_add_f32_e32 v67, v8, v67
	v_exp_f32_e32 v12, v12
	v_mul_f32_e32 v13, 0x3fb8aa3b, v13
	v_fma_f32 v14, v14, s16, -v64
	v_add_f32_e32 v67, v9, v67
	v_exp_f32_e32 v13, v13
	v_mul_f32_e32 v14, 0x3fb8aa3b, v14
	v_fma_f32 v15, v15, s16, -v64
	v_add_f32_e32 v67, v10, v67
	v_exp_f32_e32 v14, v14
	v_mul_f32_e32 v15, 0x3fb8aa3b, v15
	v_fma_f32 v16, v16, s16, -v64
	v_add_f32_e32 v67, v11, v67
	v_exp_f32_e32 v15, v15
	v_mul_f32_e32 v16, 0x3fb8aa3b, v16
	v_fma_f32 v17, v17, s16, -v64
	v_add_f32_e32 v67, v12, v67
	v_exp_f32_e32 v16, v16
	v_mul_f32_e32 v17, 0x3fb8aa3b, v17
	v_fma_f32 v18, v18, s16, -v64
	v_add_f32_e32 v67, v13, v67
	v_exp_f32_e32 v17, v17
	v_mul_f32_e32 v18, 0x3fb8aa3b, v18
	v_fma_f32 v19, v19, s16, -v64
	v_add_f32_e32 v67, v14, v67
	v_exp_f32_e32 v18, v18
	v_mul_f32_e32 v19, 0x3fb8aa3b, v19
	v_fma_f32 v20, v20, s16, -v64
	v_add_f32_e32 v67, v15, v67
	v_exp_f32_e32 v19, v19
	v_mul_f32_e32 v20, 0x3fb8aa3b, v20
	v_add_f32_e32 v67, v16, v67
	v_exp_f32_e32 v68, v20
	v_add_f32_e32 v67, v17, v67
	v_add_f32_e32 v67, v18, v67
	v_fma_f32 v21, v21, s16, -v64
	v_add_f32_e32 v67, v19, v67
	v_mul_f32_e32 v21, 0x3fb8aa3b, v21
	v_add_f32_e32 v20, v68, v67
	v_exp_f32_e32 v67, v21
	v_fma_f32 v21, v22, s16, -v64
	v_mul_f32_e32 v21, 0x3fb8aa3b, v21
	v_exp_f32_e32 v69, v21
	v_fma_f32 v21, v23, s16, -v64
	v_mul_f32_e32 v21, 0x3fb8aa3b, v21
	v_exp_f32_e32 v23, v21
	v_fma_f32 v21, v24, s16, -v64
	v_mul_f32_e32 v21, 0x3fb8aa3b, v21
	v_exp_f32_e32 v70, v21
	v_fma_f32 v21, v25, s16, -v64
	v_mul_f32_e32 v21, 0x3fb8aa3b, v21
	v_exp_f32_e32 v71, v21
	v_fma_f32 v21, v26, s16, -v64
	v_mul_f32_e32 v21, 0x3fb8aa3b, v21
	v_exp_f32_e32 v72, v21
	v_fma_f32 v21, v27, s16, -v64
	v_mul_f32_e32 v21, 0x3fb8aa3b, v21
	v_exp_f32_e32 v73, v21
	v_fma_f32 v21, v28, s16, -v64
	v_mul_f32_e32 v21, 0x3fb8aa3b, v21
	v_exp_f32_e32 v74, v21
	v_fma_f32 v21, v29, s16, -v64
	v_mul_f32_e32 v21, 0x3fb8aa3b, v21
	v_exp_f32_e32 v75, v21
	v_fma_f32 v21, v30, s16, -v64
	v_mul_f32_e32 v21, 0x3fb8aa3b, v21
	v_exp_f32_e32 v76, v21
	v_fma_f32 v21, v31, s16, -v64
	v_mul_f32_e32 v21, 0x3fb8aa3b, v21
	v_exp_f32_e32 v77, v21
	v_fma_f32 v21, v32, s16, -v64
	v_mul_f32_e32 v21, 0x3fb8aa3b, v21
	v_exp_f32_e32 v32, v21
	v_fma_f32 v21, v33, s16, -v64
	v_mul_f32_e32 v21, 0x3fb8aa3b, v21
	v_exp_f32_e32 v33, v21
	v_fma_f32 v21, v34, s16, -v64
	v_mul_f32_e32 v21, 0x3fb8aa3b, v21
; __device__ __forceinline__ unsigned cvt_pk_bf16(float lo, float hi) { unsigned r; asm volatile("v_cvt_pk_bf16_f32 %0, %1, %2" : "=v"(r) : "v"(lo), "v"(hi)); return r; }
; __device__ __forceinline__ void attnC_item(const Frame& F, const Args& a, int item) {
;     ...
;     float sum = 0.f;
; #pragma unroll
;     for (int ct = 0; ct < 16; ++ct)
; #pragma unroll
;         for (int j = 0; j < 4; ++j) { const float p = __expf(s[ct][j] - mx); s[ct][j] = p; sum += p; }
;     sum += __shfl_xor(sum, 16); sum += __shfl_xor(sum, 32);
;     bf16x8 pf[8];
; #pragma unroll
;     for (int ks = 0; ks < 8; ++ks) { u32x4 w; w.x = cvt_pk_bf16(s[2 * ks][0], s[2 * ks][1]); w.y = cvt_pk_bf16(s[2 * ks][2], s[2 * ks][3]);
;         w.z = cvt_pk_bf16(s[2 * ks + 1][0], s[2 * ks + 1][1]); w.w = cvt_pk_bf16(s[2 * ks + 1][2], s[2 * ks + 1][3]); pf[ks] = __builtin_bit_cast(bf16x8, w); }
;     __syncthreads();
	v_exp_f32_e32 v34, v21
	v_fma_f32 v21, v35, s16, -v64
	v_mul_f32_e32 v21, 0x3fb8aa3b, v21
	v_exp_f32_e32 v35, v21
	v_fma_f32 v21, v40, s16, -v64
	v_mul_f32_e32 v21, 0x3fb8aa3b, v21
	v_exp_f32_e32 v40, v21
	v_fma_f32 v21, v41, s16, -v64
	v_mul_f32_e32 v21, 0x3fb8aa3b, v21
	v_exp_f32_e32 v41, v21
	v_fma_f32 v21, v42, s16, -v64
	v_mul_f32_e32 v21, 0x3fb8aa3b, v21
	v_exp_f32_e32 v42, v21
	v_fma_f32 v21, v43, s16, -v64
	v_mul_f32_e32 v21, 0x3fb8aa3b, v21
	v_exp_f32_e32 v43, v21
	v_fma_f32 v21, v36, s16, -v64
	v_mul_f32_e32 v21, 0x3fb8aa3b, v21
	v_exp_f32_e32 v36, v21
	v_fma_f32 v21, v37, s16, -v64
	v_mul_f32_e32 v21, 0x3fb8aa3b, v21
	v_exp_f32_e32 v37, v21
	v_fma_f32 v21, v38, s16, -v64
	v_mul_f32_e32 v21, 0x3fb8aa3b, v21
	v_exp_f32_e32 v38, v21
	v_fma_f32 v21, v39, s16, -v64
	v_mul_f32_e32 v21, 0x3fb8aa3b, v21
	v_exp_f32_e32 v39, v21
	v_fma_f32 v21, v48, s16, -v64
	v_mul_f32_e32 v21, 0x3fb8aa3b, v21
	v_add_f32_e32 v20, v67, v20
	v_exp_f32_e32 v48, v21
	v_fma_f32 v21, v49, s16, -v64
	v_add_f32_e32 v20, v69, v20
	v_mul_f32_e32 v21, 0x3fb8aa3b, v21
	v_add_f32_e32 v20, v23, v20
	v_exp_f32_e32 v49, v21
	v_fma_f32 v21, v50, s16, -v64
	v_add_f32_e32 v20, v70, v20
	v_mul_f32_e32 v21, 0x3fb8aa3b, v21
	v_add_f32_e32 v20, v71, v20
	v_exp_f32_e32 v50, v21
	v_fma_f32 v21, v51, s16, -v64
	v_add_f32_e32 v20, v72, v20
	v_mul_f32_e32 v21, 0x3fb8aa3b, v21
	v_add_f32_e32 v20, v73, v20
	v_exp_f32_e32 v51, v21
	v_fma_f32 v21, v44, s16, -v64
	v_add_f32_e32 v20, v74, v20
	v_mul_f32_e32 v21, 0x3fb8aa3b, v21
	v_add_f32_e32 v20, v75, v20
	v_exp_f32_e32 v44, v21
	v_fma_f32 v21, v45, s16, -v64
	v_add_f32_e32 v20, v76, v20
	v_mul_f32_e32 v21, 0x3fb8aa3b, v21
	v_add_f32_e32 v20, v77, v20
	v_exp_f32_e32 v45, v21
	v_fma_f32 v21, v46, s16, -v64
	v_add_f32_e32 v20, v32, v20
	v_mul_f32_e32 v21, 0x3fb8aa3b, v21
	v_add_f32_e32 v20, v33, v20
	v_exp_f32_e32 v46, v21
	v_fma_f32 v21, v47, s16, -v64
	v_add_f32_e32 v20, v34, v20
	v_mul_f32_e32 v21, 0x3fb8aa3b, v21
	v_add_f32_e32 v20, v35, v20
	v_exp_f32_e32 v47, v21
	v_fma_f32 v21, v56, s16, -v64
	v_add_f32_e32 v20, v40, v20
	v_mul_f32_e32 v21, 0x3fb8aa3b, v21
	v_add_f32_e32 v20, v41, v20
	v_exp_f32_e32 v56, v21
	v_fma_f32 v21, v57, s16, -v64
	v_add_f32_e32 v20, v42, v20
	v_mul_f32_e32 v21, 0x3fb8aa3b, v21
	v_add_f32_e32 v20, v43, v20
	v_exp_f32_e32 v57, v21
	v_fma_f32 v21, v58, s16, -v64
	v_add_f32_e32 v20, v36, v20
	v_mul_f32_e32 v21, 0x3fb8aa3b, v21
	v_add_f32_e32 v20, v37, v20
	v_exp_f32_e32 v58, v21
	v_fma_f32 v21, v59, s16, -v64
	v_add_f32_e32 v20, v38, v20
	v_mul_f32_e32 v21, 0x3fb8aa3b, v21
	v_add_f32_e32 v20, v39, v20
	v_exp_f32_e32 v59, v21
	v_fma_f32 v21, v52, s16, -v64
	v_add_f32_e32 v20, v48, v20
	v_mul_f32_e32 v21, 0x3fb8aa3b, v21
	v_add_f32_e32 v20, v49, v20
	v_exp_f32_e32 v52, v21
	v_fma_f32 v21, v53, s16, -v64
	v_add_f32_e32 v20, v50, v20
	v_mul_f32_e32 v21, 0x3fb8aa3b, v21
	v_add_f32_e32 v20, v51, v20
	v_exp_f32_e32 v53, v21
	v_fma_f32 v21, v54, s16, -v64
	v_add_f32_e32 v20, v44, v20
	v_mul_f32_e32 v21, 0x3fb8aa3b, v21
	v_add_f32_e32 v20, v45, v20
	v_exp_f32_e32 v54, v21
	v_fma_f32 v21, v55, s16, -v64
	v_add_f32_e32 v20, v46, v20
	v_mul_f32_e32 v21, 0x3fb8aa3b, v21
	v_add_f32_e32 v20, v47, v20
	v_exp_f32_e32 v55, v21
	v_fma_f32 v21, v60, s16, -v64
	v_add_f32_e32 v20, v56, v20
	v_mul_f32_e32 v21, 0x3fb8aa3b, v21
	v_add_f32_e32 v20, v57, v20
	v_exp_f32_e32 v60, v21
	v_fma_f32 v21, v61, s16, -v64
	v_add_f32_e32 v20, v58, v20
	v_mul_f32_e32 v21, 0x3fb8aa3b, v21
	v_add_f32_e32 v20, v59, v20
	v_exp_f32_e32 v61, v21
	v_fma_f32 v21, v62, s16, -v64
	v_add_f32_e32 v20, v52, v20
	v_mul_f32_e32 v21, 0x3fb8aa3b, v21
	v_add_f32_e32 v20, v53, v20
	v_exp_f32_e32 v62, v21
	v_fma_f32 v21, v63, s16, -v64
	v_add_f32_e32 v20, v54, v20
	v_mul_f32_e32 v21, 0x3fb8aa3b, v21
	v_add_f32_e32 v20, v55, v20
	v_exp_f32_e32 v63, v21
	v_add_f32_e32 v20, v60, v20
	v_add_f32_e32 v20, v61, v20
	v_add_f32_e32 v20, v62, v20
	v_add_f32_e32 v20, v63, v20
	ds_bpermute_b32 v21, v66, v20
	v_cvt_pk_bf16_f32 v28, v0, v1
	v_cvt_pk_bf16_f32 v29, v2, v3
	v_cvt_pk_bf16_f32 v30, v4, v5
	v_cvt_pk_bf16_f32 v31, v6, v7
	s_waitcnt lgkmcnt(0)
	v_add_f32_e32 v96, v20, v21
	ds_bpermute_b32 v119, v65, v96
	v_cvt_pk_bf16_f32 v24, v8, v9
	v_cvt_pk_bf16_f32 v25, v10, v11
	v_cvt_pk_bf16_f32 v26, v12, v13
	v_cvt_pk_bf16_f32 v27, v14, v15
	v_cvt_pk_bf16_f32 v20, v16, v17
	v_cvt_pk_bf16_f32 v21, v18, v19
	v_cvt_pk_bf16_f32 v22, v68, v67
	v_cvt_pk_bf16_f32 v23, v69, v23
	v_cvt_pk_bf16_f32 v16, v70, v71
	v_cvt_pk_bf16_f32 v17, v72, v73
	v_cvt_pk_bf16_f32 v18, v74, v75
	v_cvt_pk_bf16_f32 v19, v76, v77
	v_cvt_pk_bf16_f32 v12, v32, v33
	v_cvt_pk_bf16_f32 v13, v34, v35
	v_cvt_pk_bf16_f32 v14, v40, v41
	v_cvt_pk_bf16_f32 v15, v42, v43
	v_cvt_pk_bf16_f32 v8, v36, v37
	v_cvt_pk_bf16_f32 v9, v38, v39
	v_cvt_pk_bf16_f32 v10, v48, v49
	v_cvt_pk_bf16_f32 v11, v50, v51
	v_cvt_pk_bf16_f32 v4, v44, v45
	v_cvt_pk_bf16_f32 v5, v46, v47
	v_cvt_pk_bf16_f32 v6, v56, v57
	v_cvt_pk_bf16_f32 v7, v58, v59
	v_cvt_pk_bf16_f32 v0, v52, v53
	v_cvt_pk_bf16_f32 v1, v54, v55
	v_cvt_pk_bf16_f32 v2, v60, v61
	v_cvt_pk_bf16_f32 v3, v62, v63
	s_waitcnt lgkmcnt(0)
	s_barrier
; #define LAS __attribute__((address_space(3)))
; __device__ __forceinline__ s16x4 vtr(const LAS char* p) { return __builtin_bit_cast(s16x4, __builtin_amdgcn_ds_read_tr16_b64_v4i16((LAS s16x4*)p)); }
; template <int NKS>
; __device__ __forceinline__ void pv_accum(f32x4 (&o)[8], const LAS unsigned char* Vt, int key_row0, const bf16x8 (&pf)[NKS], int fr, int fq) {
; #pragma unroll
;     for (int ks = 0; ks < NKS; ++ks) {
;         const LAS char* p0 = (const LAS char*)Vt + (key_row0 + 32 * ks + 4 * fq + (fr >> 2)) * AT_PITCH + 8 * (fr & 3);
; #pragma unroll
;         for (int dt = 0; dt < 8; ++dt) { const s16x4 lo = vtr(p0 + 32 * dt), hi = vtr(p0 + 16 * AT_PITCH + 32 * dt);
;             const bf16x8 vf = {lo[0], lo[1], lo[2], lo[3], hi[0], hi[1], hi[2], hi[3]};
;             o[dt] = __builtin_amdgcn_mfma_f32_16x16x32_bf16(vf, pf[ks], o[dt], 0, 0, 0); }
;         asm volatile("" ::: "memory");
;     }
; }
; __device__ __forceinline__ void attnC_item(const Frame& F, const Args& a, int item) {
;     ...
;     STAGE_TILE2(R0, (kbase + (size_t)i * 2048 + 1024), R1, (kbase + (size_t)i * 2048 + 1024 + 128));
;     __syncthreads();
;     const float inv = 1.0f / sum;
;     bf16_t* orow = (bf16_t*)a.out + qrow * YP + 2048 + head * 256;
; #pragma unroll
;     for (int half = 0; half < 2; ++half) {
;         f32x4 o[8];
; #pragma unroll
;         for (int dt = 0; dt < 8; ++dt) o[dt] = (f32x4){0.f, 0.f, 0.f, 0.f};
;         pv_accum<8>(o, half ? R1 : R0, 0, pf, fr, fq);
	global_load_dwordx4 v[32:35], v[124:125], off offset:2048
	global_load_dwordx4 v[36:39], v[124:125], off offset:2304
	global_load_dwordx4 v[40:43], v[126:127], off offset:2048
	global_load_dwordx4 v[44:47], v[126:127], off offset:2304
	global_load_dwordx4 v[48:51], v[128:129], off offset:2048
	global_load_dwordx4 v[52:55], v[128:129], off offset:2304
	global_load_dwordx4 v[56:59], v[130:131], off offset:2048
	global_load_dwordx4 v[60:63], v[130:131], off offset:2304
	global_load_dwordx4 v[64:67], v[132:133], off offset:2048
	global_load_dwordx4 v[68:71], v[132:133], off offset:2304
	global_load_dwordx4 v[72:75], v[134:135], off offset:2048
	global_load_dwordx4 v[76:79], v[134:135], off offset:2304
	global_load_dwordx4 v[80:83], v[136:137], off offset:2048
	global_load_dwordx4 v[84:87], v[136:137], off offset:2304
	global_load_dwordx4 v[88:91], v[138:139], off offset:2048
	global_load_dwordx4 v[92:95], v[138:139], off offset:2304
	s_waitcnt vmcnt(15)
	ds_write_b128 v146, v[32:35]
	s_waitcnt vmcnt(14)
	ds_write_b128 v158, v[36:39]
	s_waitcnt vmcnt(13)
	ds_write_b128 v147, v[40:43]
	s_waitcnt vmcnt(12)
	ds_write_b128 v148, v[44:47]
	s_waitcnt vmcnt(11)
	ds_write_b128 v146, v[48:51] offset:17408
	s_waitcnt vmcnt(10)
	ds_write_b128 v149, v[52:55]
	s_waitcnt vmcnt(9)
	ds_write_b128 v150, v[56:59]
	s_waitcnt vmcnt(8)
	ds_write_b128 v151, v[60:63]
	s_waitcnt vmcnt(7)
	ds_write_b128 v146, v[64:67] offset:34816
	s_waitcnt vmcnt(6)
	ds_write_b128 v152, v[68:71]
	s_waitcnt vmcnt(5)
	ds_write_b128 v153, v[72:75]
	s_waitcnt vmcnt(4)
	ds_write_b128 v154, v[76:79]
	s_waitcnt vmcnt(3)
	ds_write_b128 v146, v[80:83] offset:52224
	s_waitcnt vmcnt(2)
	ds_write_b128 v155, v[84:87]
	s_waitcnt vmcnt(1)
	ds_write_b128 v156, v[88:91]
	s_waitcnt vmcnt(0)
	ds_write_b128 v157, v[92:95]
	v_add_f32_e32 v32, v96, v119
	v_div_scale_f32 v33, s[2:3], v32, v32, 1.0
	v_rcp_f32_e32 v34, v33
	v_mov_b32_e32 v119, v97
	s_waitcnt lgkmcnt(0)
	s_barrier
	v_fma_f32 v35, -v33, v34, 1.0
	v_fmac_f32_e32 v34, v35, v34
	v_div_scale_f32 v35, vcc, 1.0, v32, 1.0
	v_mul_f32_e32 v36, v35, v34
	v_fma_f32 v37, -v33, v36, v35
	v_fmac_f32_e32 v36, v37, v34
	v_fma_f32 v33, -v33, v36, v35
	v_div_fmas_f32 v33, v33, v34, v36
	v_div_fixup_f32 v64, v33, v32, 1.0
	v_mov_b64_e32 v[32:33], s[20:21]
	v_mad_u64_u32 v[32:33], s[2:3], v122, s18, v[32:33]
	v_mad_i32_i24 v33, v123, s18, v33
	v_lshl_add_u64 v[32:33], v[32:33], 0, s[0:1]
	v_lshl_add_u64 v[62:63], v[32:33], 0, v[118:119]
	ds_read_b64_tr_b16 v[34:35], v143 offset:4352
	ds_read_b64_tr_b16 v[32:33], v143
	ds_read_b64_tr_b16 v[36:37], v143 offset:32
	ds_read_b64_tr_b16 v[38:39], v143 offset:4384
	ds_read_b64_tr_b16 v[40:41], v143 offset:64
	ds_read_b64_tr_b16 v[42:43], v143 offset:4416
	ds_read_b64_tr_b16 v[44:45], v143 offset:96
	ds_read_b64_tr_b16 v[46:47], v143 offset:4448
	ds_read_b64_tr_b16 v[48:49], v143 offset:128
	ds_read_b64_tr_b16 v[50:51], v143 offset:4480
	ds_read_b64_tr_b16 v[52:53], v143 offset:160
	ds_read_b64_tr_b16 v[54:55], v143 offset:4512
	ds_read_b64_tr_b16 v[56:57], v143 offset:192
	ds_read_b64_tr_b16 v[58:59], v143 offset:4544
	ds_read_b64_tr_b16 v[66:67], v143 offset:224
	ds_read_b64_tr_b16 v[68:69], v143 offset:4576
	s_waitcnt lgkmcnt(14)
	v_mfma_f32_16x16x32_bf16 v[32:35], v[32:35], v[28:31], 0
	ds_read_b64_tr_b16 v[72:73], v143 offset:13056
	ds_read_b64_tr_b16 v[70:71], v143 offset:8704
	ds_read_b64_tr_b16 v[74:75], v143 offset:8736
	ds_read_b64_tr_b16 v[76:77], v143 offset:13088
	v_lshl_add_u64 v[60:61], v[62:63], 0, s[8:9]
	s_waitcnt lgkmcnt(2)
	v_mfma_f32_16x16x32_bf16 v[32:35], v[70:73], v[24:27], v[32:35]
	ds_read_b64_tr_b16 v[70:71], v143 offset:8768
	ds_read_b64_tr_b16 v[72:73], v143 offset:13120
	v_add_co_u32_e32 v62, vcc, s19, v62
	v_mfma_f32_16x16x32_bf16 v[40:43], v[40:43], v[28:31], 0
	s_nop 0
	v_addc_co_u32_e32 v63, vcc, 0, v63, vcc
	s_waitcnt lgkmcnt(0)
	v_mfma_f32_16x16x32_bf16 v[40:43], v[70:73], v[24:27], v[40:43]
	ds_read_b64_tr_b16 v[70:71], v143 offset:8800
	ds_read_b64_tr_b16 v[72:73], v143 offset:13152
	v_mfma_f32_16x16x32_bf16 v[44:47], v[44:47], v[28:31], 0
	s_waitcnt lgkmcnt(0)
	v_mfma_f32_16x16x32_bf16 v[44:47], v[70:73], v[24:27], v[44:47]
	ds_read_b64_tr_b16 v[70:71], v143 offset:8832
	ds_read_b64_tr_b16 v[72:73], v143 offset:13184
	v_mfma_f32_16x16x32_bf16 v[48:51], v[48:51], v[28:31], 0
	s_waitcnt lgkmcnt(0)
	v_mfma_f32_16x16x32_bf16 v[48:51], v[70:73], v[24:27], v[48:51]
	ds_read_b64_tr_b16 v[70:71], v143 offset:8864
	ds_read_b64_tr_b16 v[72:73], v143 offset:13216
	v_mfma_f32_16x16x32_bf16 v[52:55], v[52:55], v[28:31], 0
	s_waitcnt lgkmcnt(0)
	v_mfma_f32_16x16x32_bf16 v[52:55], v[70:73], v[24:27], v[52:55]
	ds_read_b64_tr_b16 v[70:71], v143 offset:8896
	ds_read_b64_tr_b16 v[72:73], v143 offset:13248
	v_mfma_f32_16x16x32_bf16 v[56:59], v[56:59], v[28:31], 0
	s_waitcnt lgkmcnt(0)
	v_mfma_f32_16x16x32_bf16 v[56:59], v[70:73], v[24:27], v[56:59]
	ds_read_b64_tr_b16 v[70:71], v143 offset:8928
	ds_read_b64_tr_b16 v[72:73], v143 offset:13280
	v_mfma_f32_16x16x32_bf16 v[36:39], v[36:39], v[28:31], 0
	v_mfma_f32_16x16x32_bf16 v[66:69], v[66:69], v[28:31], 0
	v_mfma_f32_16x16x32_bf16 v[36:39], v[74:77], v[24:27], v[36:39]
	s_waitcnt lgkmcnt(0)
	v_mfma_f32_16x16x32_bf16 v[66:69], v[70:73], v[24:27], v[66:69]
	ds_read_b64_tr_b16 v[72:73], v143 offset:21760
	ds_read_b64_tr_b16 v[70:71], v143 offset:17408
	ds_read_b64_tr_b16 v[74:75], v143 offset:17440
	ds_read_b64_tr_b16 v[76:77], v143 offset:21792
	s_waitcnt lgkmcnt(2)
	v_mfma_f32_16x16x32_bf16 v[32:35], v[70:73], v[20:23], v[32:35]
	ds_read_b64_tr_b16 v[70:71], v143 offset:17472
	ds_read_b64_tr_b16 v[72:73], v143 offset:21824
	s_waitcnt lgkmcnt(0)
; #define LAS __attribute__((address_space(3)))
; __device__ __forceinline__ s16x4 vtr(const LAS char* p) { return __builtin_bit_cast(s16x4, __builtin_amdgcn_ds_read_tr16_b64_v4i16((LAS s16x4*)p)); }
; template <int NKS>
; __device__ __forceinline__ void pv_accum(f32x4 (&o)[8], const LAS unsigned char* Vt, int key_row0, const bf16x8 (&pf)[NKS], int fr, int fq) {
; #pragma unroll
;     for (int ks = 0; ks < NKS; ++ks) {
;         const LAS char* p0 = (const LAS char*)Vt + (key_row0 + 32 * ks + 4 * fq + (fr >> 2)) * AT_PITCH + 8 * (fr & 3);
; #pragma unroll
;         for (int dt = 0; dt < 8; ++dt) { const s16x4 lo = vtr(p0 + 32 * dt), hi = vtr(p0 + 16 * AT_PITCH + 32 * dt);
;             const bf16x8 vf = {lo[0], lo[1], lo[2], lo[3], hi[0], hi[1], hi[2], hi[3]};
;             o[dt] = __builtin_amdgcn_mfma_f32_16x16x32_bf16(vf, pf[ks], o[dt], 0, 0, 0); }
;         asm volatile("" ::: "memory");
;     }
; }
	v_mfma_f32_16x16x32_bf16 v[40:43], v[70:73], v[20:23], v[40:43]
	ds_read_b64_tr_b16 v[70:71], v143 offset:17504
	ds_read_b64_tr_b16 v[72:73], v143 offset:21856
	s_waitcnt lgkmcnt(0)
	v_mfma_f32_16x16x32_bf16 v[44:47], v[70:73], v[20:23], v[44:47]
	ds_read_b64_tr_b16 v[70:71], v143 offset:17536
	ds_read_b64_tr_b16 v[72:73], v143 offset:21888
	s_waitcnt lgkmcnt(0)
	v_mfma_f32_16x16x32_bf16 v[48:51], v[70:73], v[20:23], v[48:51]
	ds_read_b64_tr_b16 v[70:71], v143 offset:17568
	ds_read_b64_tr_b16 v[72:73], v143 offset:21920
	s_waitcnt lgkmcnt(0)
	v_mfma_f32_16x16x32_bf16 v[52:55], v[70:73], v[20:23], v[52:55]
	ds_read_b64_tr_b16 v[70:71], v143 offset:17600
	ds_read_b64_tr_b16 v[72:73], v143 offset:21952
	s_waitcnt lgkmcnt(0)
	v_mfma_f32_16x16x32_bf16 v[56:59], v[70:73], v[20:23], v[56:59]
	ds_read_b64_tr_b16 v[70:71], v143 offset:17632
	ds_read_b64_tr_b16 v[72:73], v143 offset:21984
	v_mfma_f32_16x16x32_bf16 v[36:39], v[74:77], v[20:23], v[36:39]
	s_waitcnt lgkmcnt(0)
	v_mfma_f32_16x16x32_bf16 v[66:69], v[70:73], v[20:23], v[66:69]
	ds_read_b64_tr_b16 v[72:73], v143 offset:30464
	ds_read_b64_tr_b16 v[70:71], v143 offset:26112
	ds_read_b64_tr_b16 v[74:75], v143 offset:26144
	ds_read_b64_tr_b16 v[76:77], v143 offset:30496
	s_waitcnt lgkmcnt(2)
	v_mfma_f32_16x16x32_bf16 v[32:35], v[70:73], v[16:19], v[32:35]
	ds_read_b64_tr_b16 v[70:71], v143 offset:26176
	ds_read_b64_tr_b16 v[72:73], v143 offset:30528
	s_waitcnt lgkmcnt(0)
	v_mfma_f32_16x16x32_bf16 v[40:43], v[70:73], v[16:19], v[40:43]
	ds_read_b64_tr_b16 v[70:71], v143 offset:26208
	ds_read_b64_tr_b16 v[72:73], v143 offset:30560
	s_waitcnt lgkmcnt(0)
	v_mfma_f32_16x16x32_bf16 v[44:47], v[70:73], v[16:19], v[44:47]
	ds_read_b64_tr_b16 v[70:71], v143 offset:26240
	ds_read_b64_tr_b16 v[72:73], v143 offset:30592
	s_waitcnt lgkmcnt(0)
	v_mfma_f32_16x16x32_bf16 v[48:51], v[70:73], v[16:19], v[48:51]
	ds_read_b64_tr_b16 v[70:71], v143 offset:26272
	ds_read_b64_tr_b16 v[72:73], v143 offset:30624
	s_waitcnt lgkmcnt(0)
	v_mfma_f32_16x16x32_bf16 v[52:55], v[70:73], v[16:19], v[52:55]
	ds_read_b64_tr_b16 v[70:71], v143 offset:26304
	ds_read_b64_tr_b16 v[72:73], v143 offset:30656
	s_waitcnt lgkmcnt(0)
	v_mfma_f32_16x16x32_bf16 v[56:59], v[70:73], v[16:19], v[56:59]
	ds_read_b64_tr_b16 v[70:71], v143 offset:26336
	ds_read_b64_tr_b16 v[72:73], v143 offset:30688
	v_mfma_f32_16x16x32_bf16 v[36:39], v[74:77], v[16:19], v[36:39]
	s_waitcnt lgkmcnt(0)
	v_mfma_f32_16x16x32_bf16 v[66:69], v[70:73], v[16:19], v[66:69]
	ds_read_b64_tr_b16 v[72:73], v143 offset:39168
	ds_read_b64_tr_b16 v[70:71], v143 offset:34816
	ds_read_b64_tr_b16 v[74:75], v143 offset:34848
	ds_read_b64_tr_b16 v[76:77], v143 offset:39200
	s_waitcnt lgkmcnt(2)
	v_mfma_f32_16x16x32_bf16 v[32:35], v[70:73], v[12:15], v[32:35]
	ds_read_b64_tr_b16 v[70:71], v143 offset:34880
	ds_read_b64_tr_b16 v[72:73], v143 offset:39232
	s_waitcnt lgkmcnt(0)
	v_mfma_f32_16x16x32_bf16 v[40:43], v[70:73], v[12:15], v[40:43]
	ds_read_b64_tr_b16 v[70:71], v143 offset:34912
	ds_read_b64_tr_b16 v[72:73], v143 offset:39264
	s_waitcnt lgkmcnt(0)
	v_mfma_f32_16x16x32_bf16 v[44:47], v[70:73], v[12:15], v[44:47]
	ds_read_b64_tr_b16 v[70:71], v143 offset:34944
	ds_read_b64_tr_b16 v[72:73], v143 offset:39296
	s_waitcnt lgkmcnt(0)
	v_mfma_f32_16x16x32_bf16 v[48:51], v[70:73], v[12:15], v[48:51]
	ds_read_b64_tr_b16 v[70:71], v143 offset:34976
	ds_read_b64_tr_b16 v[72:73], v143 offset:39328
	s_waitcnt lgkmcnt(0)
	v_mfma_f32_16x16x32_bf16 v[52:55], v[70:73], v[12:15], v[52:55]
	ds_read_b64_tr_b16 v[70:71], v143 offset:35008
	ds_read_b64_tr_b16 v[72:73], v143 offset:39360
	s_waitcnt lgkmcnt(0)
	v_mfma_f32_16x16x32_bf16 v[56:59], v[70:73], v[12:15], v[56:59]
	ds_read_b64_tr_b16 v[70:71], v143 offset:35040
	ds_read_b64_tr_b16 v[72:73], v143 offset:39392
	v_mfma_f32_16x16x32_bf16 v[36:39], v[74:77], v[12:15], v[36:39]
	s_waitcnt lgkmcnt(0)
	v_mfma_f32_16x16x32_bf16 v[66:69], v[70:73], v[12:15], v[66:69]
	ds_read_b64_tr_b16 v[72:73], v143 offset:47872
	ds_read_b64_tr_b16 v[70:71], v143 offset:43520
	ds_read_b64_tr_b16 v[74:75], v143 offset:43552
	ds_read_b64_tr_b16 v[76:77], v143 offset:47904
	s_waitcnt lgkmcnt(2)
	v_mfma_f32_16x16x32_bf16 v[32:35], v[70:73], v[8:11], v[32:35]
	ds_read_b64_tr_b16 v[70:71], v143 offset:43584
	ds_read_b64_tr_b16 v[72:73], v143 offset:47936
	s_waitcnt lgkmcnt(0)
	v_mfma_f32_16x16x32_bf16 v[40:43], v[70:73], v[8:11], v[40:43]
	ds_read_b64_tr_b16 v[70:71], v143 offset:43616
	ds_read_b64_tr_b16 v[72:73], v143 offset:47968
	s_waitcnt lgkmcnt(0)
	v_mfma_f32_16x16x32_bf16 v[44:47], v[70:73], v[8:11], v[44:47]
	ds_read_b64_tr_b16 v[70:71], v143 offset:43648
	ds_read_b64_tr_b16 v[72:73], v143 offset:48000
	s_waitcnt lgkmcnt(0)
	v_mfma_f32_16x16x32_bf16 v[48:51], v[70:73], v[8:11], v[48:51]
	ds_read_b64_tr_b16 v[70:71], v143 offset:43680
	ds_read_b64_tr_b16 v[72:73], v143 offset:48032
	s_waitcnt lgkmcnt(0)
	v_mfma_f32_16x16x32_bf16 v[52:55], v[70:73], v[8:11], v[52:55]
	ds_read_b64_tr_b16 v[70:71], v143 offset:43712
	ds_read_b64_tr_b16 v[72:73], v143 offset:48064
	s_waitcnt lgkmcnt(0)
	v_mfma_f32_16x16x32_bf16 v[56:59], v[70:73], v[8:11], v[56:59]
	ds_read_b64_tr_b16 v[70:71], v143 offset:43744
	ds_read_b64_tr_b16 v[72:73], v143 offset:48096
	v_mfma_f32_16x16x32_bf16 v[36:39], v[74:77], v[8:11], v[36:39]
	s_waitcnt lgkmcnt(0)
	v_mfma_f32_16x16x32_bf16 v[66:69], v[70:73], v[8:11], v[66:69]
	ds_read_b64_tr_b16 v[72:73], v143 offset:56576
	ds_read_b64_tr_b16 v[70:71], v143 offset:52224
	ds_read_b64_tr_b16 v[74:75], v143 offset:52256
	ds_read_b64_tr_b16 v[76:77], v143 offset:56608
	s_waitcnt lgkmcnt(2)
; #define LAS __attribute__((address_space(3)))
; __device__ __forceinline__ unsigned cvt_pk_bf16(float lo, float hi) { unsigned r; asm volatile("v_cvt_pk_bf16_f32 %0, %1, %2" : "=v"(r) : "v"(lo), "v"(hi)); return r; }
; __device__ __forceinline__ s16x4 vtr(const LAS char* p) { return __builtin_bit_cast(s16x4, __builtin_amdgcn_ds_read_tr16_b64_v4i16((LAS s16x4*)p)); }
; template <int NKS>
; __device__ __forceinline__ void pv_accum(f32x4 (&o)[8], const LAS unsigned char* Vt, int key_row0, const bf16x8 (&pf)[NKS], int fr, int fq) {
; #pragma unroll
;     for (int ks = 0; ks < NKS; ++ks) {
;         const LAS char* p0 = (const LAS char*)Vt + (key_row0 + 32 * ks + 4 * fq + (fr >> 2)) * AT_PITCH + 8 * (fr & 3);
; #pragma unroll
;         for (int dt = 0; dt < 8; ++dt) { const s16x4 lo = vtr(p0 + 32 * dt), hi = vtr(p0 + 16 * AT_PITCH + 32 * dt);
;             const bf16x8 vf = {lo[0], lo[1], lo[2], lo[3], hi[0], hi[1], hi[2], hi[3]};
;             o[dt] = __builtin_amdgcn_mfma_f32_16x16x32_bf16(vf, pf[ks], o[dt], 0, 0, 0); }
;         asm volatile("" ::: "memory");
;     }
; }
; __device__ __forceinline__ void attnC_item(const Frame& F, const Args& a, int item) {
;     ...
;         pv_accum<8>(o, half ? R1 : R0, 0, pf, fr, fq);
; #pragma unroll
;         for (int dt = 0; dt < 8; ++dt) { u32x2 w; w.x = cvt_pk_bf16(o[dt][0] * inv, o[dt][1] * inv); w.y = cvt_pk_bf16(o[dt][2] * inv, o[dt][3] * inv); *(u32x2*)(orow + 128 * half + 16 * dt + 4 * fq) = w; }
	v_mfma_f32_16x16x32_bf16 v[32:35], v[70:73], v[4:7], v[32:35]
	ds_read_b64_tr_b16 v[70:71], v143 offset:52288
	ds_read_b64_tr_b16 v[72:73], v143 offset:56640
	s_waitcnt lgkmcnt(0)
	v_mfma_f32_16x16x32_bf16 v[40:43], v[70:73], v[4:7], v[40:43]
	ds_read_b64_tr_b16 v[70:71], v143 offset:52320
	ds_read_b64_tr_b16 v[72:73], v143 offset:56672
	s_waitcnt lgkmcnt(0)
	v_mfma_f32_16x16x32_bf16 v[44:47], v[70:73], v[4:7], v[44:47]
	ds_read_b64_tr_b16 v[70:71], v143 offset:52352
	ds_read_b64_tr_b16 v[72:73], v143 offset:56704
	s_waitcnt lgkmcnt(0)
	v_mfma_f32_16x16x32_bf16 v[70:73], v[70:73], v[4:7], v[48:51]
	s_nop 2
	ds_read_b64_tr_b16 v[48:49], v143 offset:52384
	ds_read_b64_tr_b16 v[50:51], v143 offset:56736
	v_mfma_f32_16x16x32_bf16 v[36:39], v[74:77], v[4:7], v[36:39]
	s_waitcnt lgkmcnt(0)
	v_mfma_f32_16x16x32_bf16 v[74:77], v[48:51], v[4:7], v[52:55]
	ds_read_b64_tr_b16 v[48:49], v143 offset:52416
	ds_read_b64_tr_b16 v[50:51], v143 offset:56768
	s_waitcnt lgkmcnt(0)
	v_mfma_f32_16x16x32_bf16 v[78:81], v[48:51], v[4:7], v[56:59]
	ds_read_b64_tr_b16 v[48:49], v143 offset:52448
	ds_read_b64_tr_b16 v[50:51], v143 offset:56800
	s_waitcnt lgkmcnt(0)
	v_mfma_f32_16x16x32_bf16 v[66:69], v[48:51], v[4:7], v[66:69]
	ds_read_b64_tr_b16 v[50:51], v143 offset:65280
	ds_read_b64_tr_b16 v[48:49], v143 offset:60928
	ds_read_b64_tr_b16 v[52:53], v143 offset:60960
	ds_read_b64_tr_b16 v[54:55], v143 offset:65312
	s_waitcnt lgkmcnt(2)
	v_mfma_f32_16x16x32_bf16 v[82:85], v[48:51], v[0:3], v[32:35]
	s_nop 2
	ds_read_b64_tr_b16 v[32:33], v143 offset:60992
	ds_read_b64_tr_b16 v[34:35], v143 offset:65344
	s_nop 2
	v_mul_f32_e32 v65, v64, v82
	s_waitcnt lgkmcnt(2)
	v_mfma_f32_16x16x32_bf16 v[56:59], v[52:55], v[0:3], v[36:39]
	s_waitcnt lgkmcnt(0)
	v_mfma_f32_16x16x32_bf16 v[52:55], v[32:35], v[0:3], v[40:43]
	ds_read_b64_tr_b16 v[32:33], v143 offset:61024
	ds_read_b64_tr_b16 v[34:35], v143 offset:65376
	s_nop 3
	v_mul_f32_e32 v56, v64, v56
	v_mul_f32_e32 v57, v64, v57
	s_waitcnt lgkmcnt(0)
	v_mfma_f32_16x16x32_bf16 v[48:51], v[32:35], v[0:3], v[44:47]
	ds_read_b64_tr_b16 v[32:33], v143 offset:61056
	ds_read_b64_tr_b16 v[34:35], v143 offset:65408
	v_mul_f32_e32 v52, v64, v52
	v_mul_f32_e32 v53, v64, v53
	s_waitcnt lgkmcnt(0)
	v_mfma_f32_16x16x32_bf16 v[44:47], v[32:35], v[0:3], v[70:73]
	ds_read_b64_tr_b16 v[32:33], v143 offset:61088
	ds_read_b64_tr_b16 v[34:35], v143 offset:65440
	v_mul_f32_e32 v48, v64, v48
	v_mul_f32_e32 v49, v64, v49
	s_waitcnt lgkmcnt(0)
	v_mfma_f32_16x16x32_bf16 v[40:43], v[32:35], v[0:3], v[74:77]
	ds_read_b64_tr_b16 v[32:33], v143 offset:61120
	ds_read_b64_tr_b16 v[34:35], v143 offset:65472
	v_mul_f32_e32 v44, v64, v44
	v_mul_f32_e32 v45, v64, v45
	s_waitcnt lgkmcnt(0)
	v_mfma_f32_16x16x32_bf16 v[36:39], v[32:35], v[0:3], v[78:81]
	ds_read_b64_tr_b16 v[32:33], v143 offset:61152
	ds_read_b64_tr_b16 v[34:35], v143 offset:65504
	v_mul_f32_e32 v40, v64, v40
	s_waitcnt lgkmcnt(0)
	v_mfma_f32_16x16x32_bf16 v[32:35], v[32:35], v[0:3], v[66:69]
	v_mul_f32_e32 v41, v64, v41
	s_nop 1
	v_mul_f32_e32 v66, v64, v83
	v_mul_f32_e32 v67, v64, v85
	v_cvt_pk_bf16_f32 v66, v65, v66
	v_mul_f32_e32 v65, v64, v84
	v_cvt_pk_bf16_f32 v67, v65, v67
	global_store_dwordx2 v[62:63], v[66:67], off
	v_cvt_pk_bf16_f32 v56, v56, v57
	v_mul_f32_e32 v57, v64, v58
	v_mul_f32_e32 v58, v64, v59
	v_cvt_pk_bf16_f32 v57, v57, v58
	global_store_dwordx2 v[60:61], v[56:57], off offset:32
	v_cvt_pk_bf16_f32 v52, v52, v53
	v_mul_f32_e32 v53, v64, v54
	v_mul_f32_e32 v54, v64, v55
	v_cvt_pk_bf16_f32 v53, v53, v54
	global_store_dwordx2 v[60:61], v[52:53], off offset:64
	v_cvt_pk_bf16_f32 v48, v48, v49
	v_mul_f32_e32 v49, v64, v50
	v_mul_f32_e32 v50, v64, v51
	v_cvt_pk_bf16_f32 v49, v49, v50
	global_store_dwordx2 v[60:61], v[48:49], off offset:96
	v_cvt_pk_bf16_f32 v44, v44, v45
	v_mul_f32_e32 v45, v64, v46
	v_mul_f32_e32 v46, v64, v47
	v_cvt_pk_bf16_f32 v45, v45, v46
	global_store_dwordx2 v[60:61], v[44:45], off offset:128
	v_cvt_pk_bf16_f32 v40, v40, v41
	v_mul_f32_e32 v41, v64, v42
	v_mul_f32_e32 v36, v64, v36
	v_mul_f32_e32 v37, v64, v37
	v_mul_f32_e32 v42, v64, v43
	v_cvt_pk_bf16_f32 v41, v41, v42
	global_store_dwordx2 v[60:61], v[40:41], off offset:160
	v_cvt_pk_bf16_f32 v36, v36, v37
	v_mul_f32_e32 v37, v64, v38
	v_mul_f32_e32 v32, v64, v32
	v_mul_f32_e32 v33, v64, v33
	v_mul_f32_e32 v38, v64, v39
	v_cvt_pk_bf16_f32 v37, v37, v38
	global_store_dwordx2 v[60:61], v[36:37], off offset:192
	v_cvt_pk_bf16_f32 v32, v32, v33
	v_mul_f32_e32 v33, v64, v34
	v_mul_f32_e32 v34, v64, v35
	v_cvt_pk_bf16_f32 v33, v33, v34
	global_store_dwordx2 v[60:61], v[32:33], off offset:224
	ds_read_b64_tr_b16 v[34:35], v145 offset:4352
	ds_read_b64_tr_b16 v[32:33], v145
	ds_read_b64_tr_b16 v[36:37], v145 offset:32
	ds_read_b64_tr_b16 v[38:39], v145 offset:4384
	ds_read_b64_tr_b16 v[40:41], v145 offset:64
	ds_read_b64_tr_b16 v[42:43], v145 offset:4416
	ds_read_b64_tr_b16 v[44:45], v145 offset:96
	ds_read_b64_tr_b16 v[46:47], v145 offset:4448
	ds_read_b64_tr_b16 v[48:49], v145 offset:128
	ds_read_b64_tr_b16 v[50:51], v145 offset:4480
	ds_read_b64_tr_b16 v[52:53], v145 offset:160
	ds_read_b64_tr_b16 v[54:55], v145 offset:4512
	ds_read_b64_tr_b16 v[56:57], v145 offset:192
	ds_read_b64_tr_b16 v[58:59], v145 offset:4544
	ds_read_b64_tr_b16 v[66:67], v145 offset:224
	ds_read_b64_tr_b16 v[68:69], v145 offset:4576
	s_waitcnt lgkmcnt(14)
	v_mfma_f32_16x16x32_bf16 v[32:35], v[32:35], v[28:31], 0
	s_waitcnt lgkmcnt(12)
	v_mfma_f32_16x16x32_bf16 v[36:39], v[36:39], v[28:31], 0
	s_waitcnt lgkmcnt(10)
	v_mfma_f32_16x16x32_bf16 v[40:43], v[40:43], v[28:31], 0
	s_waitcnt lgkmcnt(8)
	v_mfma_f32_16x16x32_bf16 v[44:47], v[44:47], v[28:31], 0
	s_waitcnt lgkmcnt(6)
; #define LAS __attribute__((address_space(3)))
; __device__ __forceinline__ s16x4 vtr(const LAS char* p) { return __builtin_bit_cast(s16x4, __builtin_amdgcn_ds_read_tr16_b64_v4i16((LAS s16x4*)p)); }
; template <int NKS>
; __device__ __forceinline__ void pv_accum(f32x4 (&o)[8], const LAS unsigned char* Vt, int key_row0, const bf16x8 (&pf)[NKS], int fr, int fq) {
; #pragma unroll
;     for (int ks = 0; ks < NKS; ++ks) {
;         const LAS char* p0 = (const LAS char*)Vt + (key_row0 + 32 * ks + 4 * fq + (fr >> 2)) * AT_PITCH + 8 * (fr & 3);
; #pragma unroll
;         for (int dt = 0; dt < 8; ++dt) { const s16x4 lo = vtr(p0 + 32 * dt), hi = vtr(p0 + 16 * AT_PITCH + 32 * dt);
;             const bf16x8 vf = {lo[0], lo[1], lo[2], lo[3], hi[0], hi[1], hi[2], hi[3]};
;             o[dt] = __builtin_amdgcn_mfma_f32_16x16x32_bf16(vf, pf[ks], o[dt], 0, 0, 0); }
;         asm volatile("" ::: "memory");
;     }
; }
	v_mfma_f32_16x16x32_bf16 v[48:51], v[48:51], v[28:31], 0
	s_waitcnt lgkmcnt(4)
	v_mfma_f32_16x16x32_bf16 v[52:55], v[52:55], v[28:31], 0
	s_waitcnt lgkmcnt(2)
	v_mfma_f32_16x16x32_bf16 v[56:59], v[56:59], v[28:31], 0
	s_waitcnt lgkmcnt(0)
	v_mfma_f32_16x16x32_bf16 v[28:31], v[66:69], v[28:31], 0
	ds_read_b64_tr_b16 v[68:69], v145 offset:13056
	ds_read_b64_tr_b16 v[66:67], v145 offset:8704
	ds_read_b64_tr_b16 v[70:71], v145 offset:8736
	ds_read_b64_tr_b16 v[72:73], v145 offset:13088
	s_waitcnt lgkmcnt(2)
	v_mfma_f32_16x16x32_bf16 v[32:35], v[66:69], v[24:27], v[32:35]
	ds_read_b64_tr_b16 v[66:67], v145 offset:8768
	ds_read_b64_tr_b16 v[68:69], v145 offset:13120
	s_waitcnt lgkmcnt(0)
	v_mfma_f32_16x16x32_bf16 v[40:43], v[66:69], v[24:27], v[40:43]
	ds_read_b64_tr_b16 v[66:67], v145 offset:8800
	ds_read_b64_tr_b16 v[68:69], v145 offset:13152
	s_waitcnt lgkmcnt(0)
	v_mfma_f32_16x16x32_bf16 v[44:47], v[66:69], v[24:27], v[44:47]
	ds_read_b64_tr_b16 v[66:67], v145 offset:8832
	ds_read_b64_tr_b16 v[68:69], v145 offset:13184
	s_waitcnt lgkmcnt(0)
	v_mfma_f32_16x16x32_bf16 v[48:51], v[66:69], v[24:27], v[48:51]
	ds_read_b64_tr_b16 v[66:67], v145 offset:8864
	ds_read_b64_tr_b16 v[68:69], v145 offset:13216
	s_waitcnt lgkmcnt(0)
	v_mfma_f32_16x16x32_bf16 v[52:55], v[66:69], v[24:27], v[52:55]
	ds_read_b64_tr_b16 v[66:67], v145 offset:8896
	ds_read_b64_tr_b16 v[68:69], v145 offset:13248
	s_waitcnt lgkmcnt(0)
	v_mfma_f32_16x16x32_bf16 v[56:59], v[66:69], v[24:27], v[56:59]
	ds_read_b64_tr_b16 v[66:67], v145 offset:8928
	ds_read_b64_tr_b16 v[68:69], v145 offset:13280
	v_mfma_f32_16x16x32_bf16 v[36:39], v[70:73], v[24:27], v[36:39]
	s_waitcnt lgkmcnt(0)
	v_mfma_f32_16x16x32_bf16 v[24:27], v[66:69], v[24:27], v[28:31]
	s_nop 2
	ds_read_b64_tr_b16 v[30:31], v145 offset:21760
	ds_read_b64_tr_b16 v[28:29], v145 offset:17408
	ds_read_b64_tr_b16 v[66:67], v145 offset:17440
	ds_read_b64_tr_b16 v[68:69], v145 offset:21792
	s_waitcnt lgkmcnt(2)
	v_mfma_f32_16x16x32_bf16 v[28:31], v[28:31], v[20:23], v[32:35]
	s_waitcnt lgkmcnt(0)
	v_mfma_f32_16x16x32_bf16 v[32:35], v[66:69], v[20:23], v[36:39]
	s_nop 2
	ds_read_b64_tr_b16 v[36:37], v145 offset:17472
	ds_read_b64_tr_b16 v[38:39], v145 offset:21824
	s_waitcnt lgkmcnt(0)
	v_mfma_f32_16x16x32_bf16 v[36:39], v[36:39], v[20:23], v[40:43]
	s_nop 2
	ds_read_b64_tr_b16 v[40:41], v145 offset:17504
	ds_read_b64_tr_b16 v[42:43], v145 offset:21856
	s_waitcnt lgkmcnt(0)
	v_mfma_f32_16x16x32_bf16 v[40:43], v[40:43], v[20:23], v[44:47]
	s_nop 2
	ds_read_b64_tr_b16 v[44:45], v145 offset:17536
	ds_read_b64_tr_b16 v[46:47], v145 offset:21888
	s_waitcnt lgkmcnt(0)
	v_mfma_f32_16x16x32_bf16 v[44:47], v[44:47], v[20:23], v[48:51]
	s_nop 2
	ds_read_b64_tr_b16 v[48:49], v145 offset:17568
	ds_read_b64_tr_b16 v[50:51], v145 offset:21920
	s_waitcnt lgkmcnt(0)
	v_mfma_f32_16x16x32_bf16 v[48:51], v[48:51], v[20:23], v[52:55]
	s_nop 2
	ds_read_b64_tr_b16 v[52:53], v145 offset:17600
	ds_read_b64_tr_b16 v[54:55], v145 offset:21952
	s_waitcnt lgkmcnt(0)
	v_mfma_f32_16x16x32_bf16 v[52:55], v[52:55], v[20:23], v[56:59]
	s_nop 2
	ds_read_b64_tr_b16 v[56:57], v145 offset:17632
	ds_read_b64_tr_b16 v[58:59], v145 offset:21984
	s_waitcnt lgkmcnt(0)
	v_mfma_f32_16x16x32_bf16 v[20:23], v[56:59], v[20:23], v[24:27]
	s_nop 2
	ds_read_b64_tr_b16 v[26:27], v145 offset:30464
	ds_read_b64_tr_b16 v[24:25], v145 offset:26112
	ds_read_b64_tr_b16 v[56:57], v145 offset:26144
	ds_read_b64_tr_b16 v[58:59], v145 offset:30496
	s_waitcnt lgkmcnt(2)
	v_mfma_f32_16x16x32_bf16 v[24:27], v[24:27], v[16:19], v[28:31]
	s_waitcnt lgkmcnt(0)
	v_mfma_f32_16x16x32_bf16 v[28:31], v[56:59], v[16:19], v[32:35]
	s_nop 2
	ds_read_b64_tr_b16 v[32:33], v145 offset:26176
	ds_read_b64_tr_b16 v[34:35], v145 offset:30528
	s_waitcnt lgkmcnt(0)
	v_mfma_f32_16x16x32_bf16 v[32:35], v[32:35], v[16:19], v[36:39]
	s_nop 2
	ds_read_b64_tr_b16 v[36:37], v145 offset:26208
	ds_read_b64_tr_b16 v[38:39], v145 offset:30560
	s_waitcnt lgkmcnt(0)
	v_mfma_f32_16x16x32_bf16 v[36:39], v[36:39], v[16:19], v[40:43]
	s_nop 2
	ds_read_b64_tr_b16 v[40:41], v145 offset:26240
	ds_read_b64_tr_b16 v[42:43], v145 offset:30592
	s_waitcnt lgkmcnt(0)
	v_mfma_f32_16x16x32_bf16 v[40:43], v[40:43], v[16:19], v[44:47]
	s_nop 2
	ds_read_b64_tr_b16 v[44:45], v145 offset:26272
	ds_read_b64_tr_b16 v[46:47], v145 offset:30624
	s_waitcnt lgkmcnt(0)
	v_mfma_f32_16x16x32_bf16 v[44:47], v[44:47], v[16:19], v[48:51]
	s_nop 2
	ds_read_b64_tr_b16 v[48:49], v145 offset:26304
	ds_read_b64_tr_b16 v[50:51], v145 offset:30656
	s_waitcnt lgkmcnt(0)
	v_mfma_f32_16x16x32_bf16 v[48:51], v[48:51], v[16:19], v[52:55]
	s_nop 2
	ds_read_b64_tr_b16 v[52:53], v145 offset:26336
	ds_read_b64_tr_b16 v[54:55], v145 offset:30688
	s_waitcnt lgkmcnt(0)
	v_mfma_f32_16x16x32_bf16 v[16:19], v[52:55], v[16:19], v[20:23]
	s_nop 2
	ds_read_b64_tr_b16 v[22:23], v145 offset:39168
	ds_read_b64_tr_b16 v[20:21], v145 offset:34816
	ds_read_b64_tr_b16 v[52:53], v145 offset:34848
	ds_read_b64_tr_b16 v[54:55], v145 offset:39200
	s_waitcnt lgkmcnt(2)
	v_mfma_f32_16x16x32_bf16 v[20:23], v[20:23], v[12:15], v[24:27]
	s_waitcnt lgkmcnt(0)
	v_mfma_f32_16x16x32_bf16 v[24:27], v[52:55], v[12:15], v[28:31]
	s_nop 2
	ds_read_b64_tr_b16 v[28:29], v145 offset:34880
	ds_read_b64_tr_b16 v[30:31], v145 offset:39232
	s_waitcnt lgkmcnt(0)
	v_mfma_f32_16x16x32_bf16 v[28:31], v[28:31], v[12:15], v[32:35]
	s_nop 2
	ds_read_b64_tr_b16 v[32:33], v145 offset:34912
	ds_read_b64_tr_b16 v[34:35], v145 offset:39264
	s_waitcnt lgkmcnt(0)
	v_mfma_f32_16x16x32_bf16 v[32:35], v[32:35], v[12:15], v[36:39]
	s_nop 2
	ds_read_b64_tr_b16 v[36:37], v145 offset:34944
	ds_read_b64_tr_b16 v[38:39], v145 offset:39296
	s_waitcnt lgkmcnt(0)
; __device__ __forceinline__ unsigned cvt_pk_bf16(float lo, float hi) { unsigned r; asm volatile("v_cvt_pk_bf16_f32 %0, %1, %2" : "=v"(r) : "v"(lo), "v"(hi)); return r; }
; __device__ __forceinline__ void attnC_item(const Frame& F, const Args& a, int item) {
;     ...
;     for (int half = 0; half < 2; ++half) {
;         f32x4 o[8];
; #pragma unroll
;         for (int dt = 0; dt < 8; ++dt) o[dt] = (f32x4){0.f, 0.f, 0.f, 0.f};
;         pv_accum<8>(o, half ? R1 : R0, 0, pf, fr, fq);
; #pragma unroll
;         for (int dt = 0; dt < 8; ++dt) { u32x2 w; w.x = cvt_pk_bf16(o[dt][0] * inv, o[dt][1] * inv); w.y = cvt_pk_bf16(o[dt][2] * inv, o[dt][3] * inv); *(u32x2*)(orow + 128 * half + 16 * dt + 4 * fq) = w; }
	v_mfma_f32_16x16x32_bf16 v[36:39], v[36:39], v[12:15], v[40:43]
	s_nop 2
	ds_read_b64_tr_b16 v[40:41], v145 offset:34976
	ds_read_b64_tr_b16 v[42:43], v145 offset:39328
	s_waitcnt lgkmcnt(0)
	v_mfma_f32_16x16x32_bf16 v[40:43], v[40:43], v[12:15], v[44:47]
	s_nop 2
	ds_read_b64_tr_b16 v[44:45], v145 offset:35008
	ds_read_b64_tr_b16 v[46:47], v145 offset:39360
	s_waitcnt lgkmcnt(0)
	v_mfma_f32_16x16x32_bf16 v[44:47], v[44:47], v[12:15], v[48:51]
	s_nop 2
	ds_read_b64_tr_b16 v[48:49], v145 offset:35040
	ds_read_b64_tr_b16 v[50:51], v145 offset:39392
	s_waitcnt lgkmcnt(0)
	v_mfma_f32_16x16x32_bf16 v[12:15], v[48:51], v[12:15], v[16:19]
	s_nop 2
	ds_read_b64_tr_b16 v[18:19], v145 offset:47872
	ds_read_b64_tr_b16 v[16:17], v145 offset:43520
	ds_read_b64_tr_b16 v[48:49], v145 offset:43552
	ds_read_b64_tr_b16 v[50:51], v145 offset:47904
	s_waitcnt lgkmcnt(2)
	v_mfma_f32_16x16x32_bf16 v[16:19], v[16:19], v[8:11], v[20:23]
	s_waitcnt lgkmcnt(0)
	v_mfma_f32_16x16x32_bf16 v[20:23], v[48:51], v[8:11], v[24:27]
	s_nop 2
	ds_read_b64_tr_b16 v[24:25], v145 offset:43584
	ds_read_b64_tr_b16 v[26:27], v145 offset:47936
	s_waitcnt lgkmcnt(0)
	v_mfma_f32_16x16x32_bf16 v[24:27], v[24:27], v[8:11], v[28:31]
	s_nop 2
	ds_read_b64_tr_b16 v[28:29], v145 offset:43616
	ds_read_b64_tr_b16 v[30:31], v145 offset:47968
	s_waitcnt lgkmcnt(0)
	v_mfma_f32_16x16x32_bf16 v[28:31], v[28:31], v[8:11], v[32:35]
	s_nop 2
	ds_read_b64_tr_b16 v[32:33], v145 offset:43648
	ds_read_b64_tr_b16 v[34:35], v145 offset:48000
	s_waitcnt lgkmcnt(0)
	v_mfma_f32_16x16x32_bf16 v[32:35], v[32:35], v[8:11], v[36:39]
	s_nop 2
	ds_read_b64_tr_b16 v[36:37], v145 offset:43680
	ds_read_b64_tr_b16 v[38:39], v145 offset:48032
	s_waitcnt lgkmcnt(0)
	v_mfma_f32_16x16x32_bf16 v[36:39], v[36:39], v[8:11], v[40:43]
	s_nop 2
	ds_read_b64_tr_b16 v[40:41], v145 offset:43712
	ds_read_b64_tr_b16 v[42:43], v145 offset:48064
	s_waitcnt lgkmcnt(0)
	v_mfma_f32_16x16x32_bf16 v[40:43], v[40:43], v[8:11], v[44:47]
	s_nop 2
	ds_read_b64_tr_b16 v[44:45], v145 offset:43744
	ds_read_b64_tr_b16 v[46:47], v145 offset:48096
	s_waitcnt lgkmcnt(0)
	v_mfma_f32_16x16x32_bf16 v[8:11], v[44:47], v[8:11], v[12:15]
	s_nop 2
	ds_read_b64_tr_b16 v[14:15], v145 offset:56576
	ds_read_b64_tr_b16 v[12:13], v145 offset:52224
	ds_read_b64_tr_b16 v[44:45], v145 offset:52256
	ds_read_b64_tr_b16 v[46:47], v145 offset:56608
	s_waitcnt lgkmcnt(2)
	v_mfma_f32_16x16x32_bf16 v[12:15], v[12:15], v[4:7], v[16:19]
	s_waitcnt lgkmcnt(0)
	v_mfma_f32_16x16x32_bf16 v[16:19], v[44:47], v[4:7], v[20:23]
	s_nop 2
	ds_read_b64_tr_b16 v[20:21], v145 offset:52288
	ds_read_b64_tr_b16 v[22:23], v145 offset:56640
	s_waitcnt lgkmcnt(0)
	v_mfma_f32_16x16x32_bf16 v[20:23], v[20:23], v[4:7], v[24:27]
	s_nop 2
	ds_read_b64_tr_b16 v[24:25], v145 offset:52320
	ds_read_b64_tr_b16 v[26:27], v145 offset:56672
	s_waitcnt lgkmcnt(0)
	v_mfma_f32_16x16x32_bf16 v[24:27], v[24:27], v[4:7], v[28:31]
	s_nop 2
	ds_read_b64_tr_b16 v[28:29], v145 offset:52352
	ds_read_b64_tr_b16 v[30:31], v145 offset:56704
	s_waitcnt lgkmcnt(0)
	v_mfma_f32_16x16x32_bf16 v[28:31], v[28:31], v[4:7], v[32:35]
	s_nop 2
	ds_read_b64_tr_b16 v[32:33], v145 offset:52384
	ds_read_b64_tr_b16 v[34:35], v145 offset:56736
	s_waitcnt lgkmcnt(0)
	v_mfma_f32_16x16x32_bf16 v[32:35], v[32:35], v[4:7], v[36:39]
	s_nop 2
	ds_read_b64_tr_b16 v[36:37], v145 offset:52416
	ds_read_b64_tr_b16 v[38:39], v145 offset:56768
	s_waitcnt lgkmcnt(0)
	v_mfma_f32_16x16x32_bf16 v[36:39], v[36:39], v[4:7], v[40:43]
	s_nop 2
	ds_read_b64_tr_b16 v[40:41], v145 offset:52448
	ds_read_b64_tr_b16 v[42:43], v145 offset:56800
	s_waitcnt lgkmcnt(0)
	v_mfma_f32_16x16x32_bf16 v[4:7], v[40:43], v[4:7], v[8:11]
	s_nop 2
	ds_read_b64_tr_b16 v[10:11], v145 offset:65280
	ds_read_b64_tr_b16 v[8:9], v145 offset:60928
	ds_read_b64_tr_b16 v[40:41], v145 offset:60960
	ds_read_b64_tr_b16 v[42:43], v145 offset:65312
	s_waitcnt lgkmcnt(2)
	v_mfma_f32_16x16x32_bf16 v[8:11], v[8:11], v[0:3], v[12:15]
	s_waitcnt lgkmcnt(0)
	v_mfma_f32_16x16x32_bf16 v[12:15], v[40:43], v[0:3], v[16:19]
	s_nop 2
	ds_read_b64_tr_b16 v[16:17], v145 offset:60992
	ds_read_b64_tr_b16 v[18:19], v145 offset:65344
	s_waitcnt lgkmcnt(0)
	v_mfma_f32_16x16x32_bf16 v[16:19], v[16:19], v[0:3], v[20:23]
	s_nop 2
	ds_read_b64_tr_b16 v[20:21], v145 offset:61024
	ds_read_b64_tr_b16 v[22:23], v145 offset:65376
	s_waitcnt lgkmcnt(0)
	v_mfma_f32_16x16x32_bf16 v[20:23], v[20:23], v[0:3], v[24:27]
	s_nop 2
	ds_read_b64_tr_b16 v[24:25], v145 offset:61056
	ds_read_b64_tr_b16 v[26:27], v145 offset:65408
	s_waitcnt lgkmcnt(0)
	v_mfma_f32_16x16x32_bf16 v[24:27], v[24:27], v[0:3], v[28:31]
	s_nop 2
	ds_read_b64_tr_b16 v[28:29], v145 offset:61088
	ds_read_b64_tr_b16 v[30:31], v145 offset:65440
	s_waitcnt lgkmcnt(0)
	v_mfma_f32_16x16x32_bf16 v[28:31], v[28:31], v[0:3], v[32:35]
	s_nop 2
	ds_read_b64_tr_b16 v[32:33], v145 offset:61120
	ds_read_b64_tr_b16 v[34:35], v145 offset:65472
	s_waitcnt lgkmcnt(0)
	v_mfma_f32_16x16x32_bf16 v[32:35], v[32:35], v[0:3], v[36:39]
	s_nop 2
	ds_read_b64_tr_b16 v[36:37], v145 offset:61152
	ds_read_b64_tr_b16 v[38:39], v145 offset:65504
	s_waitcnt lgkmcnt(0)
	v_mfma_f32_16x16x32_bf16 v[0:3], v[36:39], v[0:3], v[4:7]
	s_nop 2
	v_mul_f32_e32 v4, v64, v8
	v_mul_f32_e32 v5, v64, v9
	v_cvt_pk_bf16_f32 v4, v4, v5
	v_mul_f32_e32 v5, v64, v10
	v_mul_f32_e32 v6, v64, v11
	v_cvt_pk_bf16_f32 v5, v5, v6
	global_store_dwordx2 v[60:61], v[4:5], off offset:256
	v_mul_f32_e32 v4, v64, v12
	v_mul_f32_e32 v5, v64, v13
	v_cvt_pk_bf16_f32 v4, v4, v5
	v_mul_f32_e32 v5, v64, v14
	v_mul_f32_e32 v6, v64, v15
	v_cvt_pk_bf16_f32 v5, v5, v6
	global_store_dwordx2 v[60:61], v[4:5], off offset:288
	v_mul_f32_e32 v4, v64, v16
	v_mul_f32_e32 v5, v64, v17
	v_cvt_pk_bf16_f32 v4, v4, v5
	v_mul_f32_e32 v5, v64, v18
	v_mul_f32_e32 v6, v64, v19
	v_cvt_pk_bf16_f32 v5, v5, v6
	global_store_dwordx2 v[60:61], v[4:5], off offset:320
	v_mul_f32_e32 v4, v64, v20
	v_mul_f32_e32 v5, v64, v21
	v_cvt_pk_bf16_f32 v4, v4, v5
	v_mul_f32_e32 v5, v64, v22
	v_mul_f32_e32 v6, v64, v23
	v_cvt_pk_bf16_f32 v5, v5, v6
	global_store_dwordx2 v[60:61], v[4:5], off offset:352
	v_mul_f32_e32 v4, v64, v24
	v_mul_f32_e32 v5, v64, v25
	v_cvt_pk_bf16_f32 v4, v4, v5
	v_mul_f32_e32 v5, v64, v26
	v_mul_f32_e32 v6, v64, v27
	v_cvt_pk_bf16_f32 v5, v5, v6
	global_store_dwordx2 v[60:61], v[4:5], off offset:384
	v_mul_f32_e32 v4, v64, v28
	v_mul_f32_e32 v5, v64, v29
	v_cvt_pk_bf16_f32 v4, v4, v5
	v_mul_f32_e32 v5, v64, v30
	v_mul_f32_e32 v6, v64, v31
	v_cvt_pk_bf16_f32 v5, v5, v6
	global_store_dwordx2 v[60:61], v[4:5], off offset:416
	v_mul_f32_e32 v4, v64, v32
	v_mul_f32_e32 v5, v64, v33
	v_cvt_pk_bf16_f32 v4, v4, v5
	v_mul_f32_e32 v5, v64, v34
	v_mul_f32_e32 v0, v64, v0
	v_mul_f32_e32 v1, v64, v1
	v_mul_f32_e32 v6, v64, v35
	v_cvt_pk_bf16_f32 v5, v5, v6
	global_store_dwordx2 v[60:61], v[4:5], off offset:448
	v_cvt_pk_bf16_f32 v0, v0, v1
	v_mul_f32_e32 v1, v64, v2
	v_mul_f32_e32 v2, v64, v3
	v_cvt_pk_bf16_f32 v1, v1, v2
	global_store_dwordx2 v[60:61], v[0:1], off offset:480
	s_cbranch_scc0 .LBB0_396

; __device__ __forceinline__ void attnA_item(const Frame& F, const Args& a, int item) {
;     ...
;     const int qq = 16 * (F.wave & 3) + fr;
;     const int qpos = (n0 + hb) * 64 + qq;
;     const size_t qrow = rowbase + (size_t)qpos * d + r;
;     bf16x8 qf[4];
; #pragma unroll
;     for (int ks = 0; ks < 4; ++ks) qf[ks] = *(const bf16x8*)(proj + qrow * NIN + C_Q + h * 128 + 32 * ks + 8 * fq);
;     __syncthreads();
.LBB0_468:
	s_or_b64 exec, exec, s[72:73]
	s_add_i32 s12, s12, s95
	v_or_b32_e32 v66, s12, v86
	v_lshlrev_b64 v[0:1], s11, v[66:67]
	v_lshl_add_u64 v[60:61], v[0:1], 0, s[8:9]
	v_mov_b64_e32 v[0:1], s[96:97]
	v_mad_u64_u32 v[0:1], s[8:9], v60, s93, v[0:1]
	v_mov_b32_e32 v2, v1
	v_mad_u64_u32 v[2:3], s[8:9], v61, s93, v[2:3]
	v_mov_b32_e32 v1, v2
	v_lshl_add_u64 v[0:1], s[2:3], 1, v[0:1]
	v_mov_b32_e32 v71, v67
	v_lshl_add_u64 v[0:1], v[0:1], 0, v[70:71]
	global_load_dwordx4 v[56:59], v[0:1], off
	global_load_dwordx4 v[52:55], v[0:1], off offset:64
	global_load_dwordx4 v[48:51], v[0:1], off offset:128
	s_nop 0
	global_load_dwordx4 v[0:3], v[0:1], off offset:192
	s_waitcnt lgkmcnt(0)
	s_barrier
; #define LAS __attribute__((address_space(3)))
; template <int NCT>
; __device__ __forceinline__ void qk_accum(f32x4 (&s)[NCT], const LAS unsigned char* Kt, int key_row0, const bf16x8 (&qf)[4], int fr, int fq) {
; #pragma unroll
;     for (int ct = 0; ct < NCT; ++ct)
; #pragma unroll
;         for (int ks = 0; ks < 4; ++ks) { const bf16x8 kf = *(const LAS bf16x8*)(Kt + (key_row0 + 16 * ct + fr) * AT_PITCH + 64 * ks + 16 * fq);
;             s[ct] = __builtin_amdgcn_mfma_f32_16x16x32_bf16(kf, qf[ks], s[ct], 0, 0, 0); if (ks == 3 && (ct & 1)) asm volatile("" ::: "memory"); }
; }
	s_sub_i32 s3, s12, 64
	s_cmp_lg_u32 s12, 0
	v_readlane_b32 s14, v242, 44
	s_cselect_b64 s[8:9], -1, 0
	v_readlane_b32 s15, v242, 45
	s_and_b64 s[14:15], s[14:15], s[8:9]
	ds_read_b128 v[208:211], v196
	ds_read_b128 v[212:215], v196 offset:64
	ds_read_b128 v[216:219], v196 offset:128
	ds_read_b128 v[220:223], v196 offset:192
	ds_read_b128 v[224:227], v196 offset:4352
	ds_read_b128 v[228:231], v196 offset:4416
	ds_read_b128 v[232:235], v196 offset:4480
	ds_read_b128 v[236:239], v196 offset:4544
	ds_read_b128 v[244:247], v196 offset:8704
	ds_read_b128 v[248:251], v196 offset:8768
	ds_read_b128 v[252:255], v196 offset:8832
	s_waitcnt vmcnt(0)
	s_waitcnt lgkmcnt(10)
	v_mfma_f32_16x16x32_bf16 v[4:7], v[208:211], v[56:59], 0
	ds_read_b128 v[208:211], v196 offset:8896
	s_waitcnt lgkmcnt(10)
	v_mfma_f32_16x16x32_bf16 v[4:7], v[212:215], v[52:55], v[4:7]
	ds_read_b128 v[212:215], v196 offset:13056
	s_waitcnt lgkmcnt(10)
	v_mfma_f32_16x16x32_bf16 v[4:7], v[216:219], v[48:51], v[4:7]
	ds_read_b128 v[216:219], v196 offset:13120
	s_waitcnt lgkmcnt(10)
	v_mfma_f32_16x16x32_bf16 v[44:47], v[220:223], v[0:3], v[4:7]
	ds_read_b128 v[220:223], v196 offset:13184
	s_waitcnt lgkmcnt(10)
	v_mfma_f32_16x16x32_bf16 v[4:7], v[224:227], v[56:59], 0
	ds_read_b128 v[224:227], v196 offset:13248
	s_waitcnt lgkmcnt(10)
	v_mfma_f32_16x16x32_bf16 v[4:7], v[228:231], v[52:55], v[4:7]
	ds_read_b128 v[228:231], v196 offset:17408
	s_waitcnt lgkmcnt(10)
	v_mfma_f32_16x16x32_bf16 v[4:7], v[232:235], v[48:51], v[4:7]
	ds_read_b128 v[232:235], v196 offset:17472
	s_waitcnt lgkmcnt(10)
	v_mfma_f32_16x16x32_bf16 v[40:43], v[236:239], v[0:3], v[4:7]
	ds_read_b128 v[236:239], v196 offset:17536
	s_waitcnt lgkmcnt(10)
	v_mfma_f32_16x16x32_bf16 v[4:7], v[244:247], v[56:59], 0
	ds_read_b128 v[244:247], v196 offset:17600
	s_waitcnt lgkmcnt(10)
	v_mfma_f32_16x16x32_bf16 v[4:7], v[248:251], v[52:55], v[4:7]
	ds_read_b128 v[248:251], v196 offset:21760
	s_waitcnt lgkmcnt(10)
	v_mfma_f32_16x16x32_bf16 v[4:7], v[252:255], v[48:51], v[4:7]
	ds_read_b128 v[252:255], v196 offset:21824
	s_waitcnt lgkmcnt(10)
	v_mfma_f32_16x16x32_bf16 v[36:39], v[208:211], v[0:3], v[4:7]
	ds_read_b128 v[208:211], v196 offset:21888
	s_waitcnt lgkmcnt(10)
	v_mfma_f32_16x16x32_bf16 v[4:7], v[212:215], v[56:59], 0
	ds_read_b128 v[212:215], v196 offset:21952
	s_waitcnt lgkmcnt(10)
	v_mfma_f32_16x16x32_bf16 v[4:7], v[216:219], v[52:55], v[4:7]
	ds_read_b128 v[216:219], v196 offset:26112
	s_waitcnt lgkmcnt(10)
	v_mfma_f32_16x16x32_bf16 v[4:7], v[220:223], v[48:51], v[4:7]
	ds_read_b128 v[220:223], v196 offset:26176
	s_waitcnt lgkmcnt(10)
	v_mfma_f32_16x16x32_bf16 v[32:35], v[224:227], v[0:3], v[4:7]
	ds_read_b128 v[224:227], v196 offset:26240
	s_waitcnt lgkmcnt(10)
	v_mfma_f32_16x16x32_bf16 v[4:7], v[228:231], v[56:59], 0
	ds_read_b128 v[228:231], v196 offset:26304
	s_waitcnt lgkmcnt(10)
	v_mfma_f32_16x16x32_bf16 v[4:7], v[232:235], v[52:55], v[4:7]
	ds_read_b128 v[232:235], v196 offset:30464
	s_waitcnt lgkmcnt(10)
	v_mfma_f32_16x16x32_bf16 v[4:7], v[236:239], v[48:51], v[4:7]
	ds_read_b128 v[236:239], v196 offset:30528
	s_waitcnt lgkmcnt(10)
	v_mfma_f32_16x16x32_bf16 v[20:23], v[244:247], v[0:3], v[4:7]
	ds_read_b128 v[244:247], v196 offset:30592
	s_waitcnt lgkmcnt(10)
	v_mfma_f32_16x16x32_bf16 v[4:7], v[248:251], v[56:59], 0
	ds_read_b128 v[248:251], v196 offset:30656
	s_waitcnt lgkmcnt(10)
	v_mfma_f32_16x16x32_bf16 v[4:7], v[252:255], v[52:55], v[4:7]
	ds_read_b128 v[252:255], v196 offset:34816
	s_waitcnt lgkmcnt(10)
	v_mfma_f32_16x16x32_bf16 v[4:7], v[208:211], v[48:51], v[4:7]
	ds_read_b128 v[208:211], v196 offset:34880
	s_waitcnt lgkmcnt(10)
	v_mfma_f32_16x16x32_bf16 v[16:19], v[212:215], v[0:3], v[4:7]
	ds_read_b128 v[212:215], v196 offset:34944
	s_waitcnt lgkmcnt(10)
	v_mfma_f32_16x16x32_bf16 v[4:7], v[216:219], v[56:59], 0
	ds_read_b128 v[216:219], v196 offset:35008
	s_waitcnt lgkmcnt(10)
	v_mfma_f32_16x16x32_bf16 v[4:7], v[220:223], v[52:55], v[4:7]
	ds_read_b128 v[220:223], v196 offset:39168
	s_waitcnt lgkmcnt(10)
	v_mfma_f32_16x16x32_bf16 v[4:7], v[224:227], v[48:51], v[4:7]
	ds_read_b128 v[224:227], v196 offset:39232
	s_waitcnt lgkmcnt(10)
	v_mfma_f32_16x16x32_bf16 v[28:31], v[228:231], v[0:3], v[4:7]
	ds_read_b128 v[228:231], v196 offset:39296
	s_waitcnt lgkmcnt(10)
	v_mfma_f32_16x16x32_bf16 v[4:7], v[232:235], v[56:59], 0
	ds_read_b128 v[232:235], v196 offset:39360
	s_waitcnt lgkmcnt(10)
	v_mfma_f32_16x16x32_bf16 v[4:7], v[236:239], v[52:55], v[4:7]
	ds_read_b128 v[236:239], v196 offset:43584
	s_waitcnt lgkmcnt(10)
	v_mfma_f32_16x16x32_bf16 v[4:7], v[244:247], v[48:51], v[4:7]
	ds_read_b128 v[244:247], v196 offset:43520
	s_waitcnt lgkmcnt(10)
	v_mfma_f32_16x16x32_bf16 v[24:27], v[248:251], v[0:3], v[4:7]
	ds_read_b128 v[248:251], v196 offset:43648
	s_waitcnt lgkmcnt(10)
	v_mfma_f32_16x16x32_bf16 v[4:7], v[252:255], v[56:59], 0
	ds_read_b128 v[252:255], v196 offset:43712
	s_waitcnt lgkmcnt(10)
	v_mfma_f32_16x16x32_bf16 v[4:7], v[208:211], v[52:55], v[4:7]
	ds_read_b128 v[208:211], v196 offset:47872
	s_waitcnt lgkmcnt(10)
	v_mfma_f32_16x16x32_bf16 v[4:7], v[212:215], v[48:51], v[4:7]
	ds_read_b128 v[212:215], v196 offset:47936
	s_waitcnt lgkmcnt(10)
	v_mfma_f32_16x16x32_bf16 v[12:15], v[216:219], v[0:3], v[4:7]
	ds_read_b128 v[216:219], v196 offset:48000
	s_waitcnt lgkmcnt(10)
	v_mfma_f32_16x16x32_bf16 v[4:7], v[220:223], v[56:59], 0
	ds_read_b128 v[220:223], v196 offset:48064
	s_waitcnt lgkmcnt(10)
	v_mfma_f32_16x16x32_bf16 v[4:7], v[224:227], v[52:55], v[4:7]
	s_waitcnt lgkmcnt(9)
	v_mfma_f32_16x16x32_bf16 v[4:7], v[228:231], v[48:51], v[4:7]
	s_waitcnt lgkmcnt(8)
	v_mfma_f32_16x16x32_bf16 v[8:11], v[232:235], v[0:3], v[4:7]
	s_waitcnt lgkmcnt(6)
	v_mfma_f32_16x16x32_bf16 v[4:7], v[244:247], v[56:59], 0
	s_waitcnt lgkmcnt(7)
	v_mfma_f32_16x16x32_bf16 v[4:7], v[236:239], v[52:55], v[4:7]
	s_waitcnt lgkmcnt(5)
	v_mfma_f32_16x16x32_bf16 v[4:7], v[248:251], v[48:51], v[4:7]
	s_waitcnt lgkmcnt(4)
	v_mfma_f32_16x16x32_bf16 v[4:7], v[252:255], v[0:3], v[4:7]
	s_waitcnt lgkmcnt(3)
	v_mfma_f32_16x16x32_bf16 v[56:59], v[208:211], v[56:59], 0
	s_waitcnt lgkmcnt(2)
	v_mfma_f32_16x16x32_bf16 v[52:55], v[212:215], v[52:55], v[56:59]
	s_waitcnt lgkmcnt(1)
	v_mfma_f32_16x16x32_bf16 v[48:51], v[216:219], v[48:51], v[52:55]
	s_waitcnt lgkmcnt(0)
	v_mfma_f32_16x16x32_bf16 v[0:3], v[220:223], v[0:3], v[48:51]
	s_nop 2
	v_or_b32_e32 v48, s3, v68
	v_cmp_gt_i32_e32 vcc, s10, v48
	s_and_b64 s[14:15], s[14:15], vcc
	v_mov_b32_e32 v48, 0xf149f2ca
	v_mov_b32_e32 v49, 0xf149f2ca
	s_and_saveexec_b64 s[72:73], s[14:15]
	s_cbranch_execz .LBB0_470
	ds_read_b32 v49, v87
	s_waitcnt lgkmcnt(0)
	v_fmac_f32_e32 v49, 0x3db504f3, v44
